# w_in GEMM epilogue (gelu + LayerNorm partial stats) regenerated with the parametric epilogue generator: packed math, permlane butterflies, batched loads
# baseline (speedup 1.0000x reference)
;     __device__ __forceinline__ void operator()(const f32x4 (&acc)[2][2][4][2], const Unit& u, int wr, int wc, int fr, int fq) const {
;         const int rowt = u.pm * BM, b = rowt >= MLAT ? 2 : (rowt >> 13);
;         const int row0 = rowt + wr * 64 + fr, col0 = u.pn * BM + wc * 32 + 8 * fq;
;         f32x4 bv[2][2];
; #pragma unroll
;         for (int bj = 0; bj < 2; ++bj)
; #pragma unroll
;             for (int n = 0; n < 2; ++n) bv[bj][n] = *(const f32x4*)(bias + (size_t)b * nbias + col0 + bj * HALF + 4 * n);
;         float rsv[2][4];
;         { f32x4 pq[2][4];
; #pragma unroll
;           for (int ai = 0; ai < 2; ++ai)
; #pragma unroll
;               for (int m = 0; m < 4; ++m) pq[ai][m] = *(const f32x4*)(ssq + (size_t)(row0 + ai * HALF + m * 16) * 16 + 4 * fq);
; #pragma unroll
;           for (int ai = 0; ai < 2; ++ai)
; #pragma unroll
;               for (int m = 0; m < 4; ++m) { float t = (pq[ai][m][0] + pq[ai][m][1]) + (pq[ai][m][2] + pq[ai][m][3]); t += __shfl_xor(t, 16); t += __shfl_xor(t, 32);
;                   rsv[ai][m] = rsqrtf(t * (1.f / DM) + EPS); } }
; #pragma unroll
;         for (int ai = 0; ai < 2; ++ai)
; #pragma unroll
;             for (int m = 0; m < 4; ++m) { const int row = row0 + ai * HALF + m * 16; bf16_t* rowp = O + (size_t)row * ldc + col0; float s = 0.f, q = 0.f;
.LBB0_186:
	s_min_i32 s16, s36, 64
	s_ashr_i32 s16, s16, 5
	s_lshl_b32 s16, s16, 14
	s_add_u32 s42, s62, s16
	s_addc_u32 s43, s63, 0
	v_lshl_add_u32 v196, s36, 8, v201
	v_lshl_or_b32 v200, s44, 8, v203
	v_mov_b32_e32 v197, 0
	v_lshlrev_b32_e32 v205, 2, v200
	v_lshlrev_b64 v[198:199], 6, v[196:197]
	v_lshl_add_u64 v[198:199], v[198:199], 0, v[174:175]
	global_load_dwordx4 v[32:35], v205, s[42:43] offset:0
	global_load_dwordx4 v[36:39], v205, s[42:43] offset:16
	global_load_dwordx4 v[40:43], v205, s[42:43] offset:512
	global_load_dwordx4 v[44:47], v205, s[42:43] offset:528
	s_mov_b64 s[16:17], 0x2000
	v_lshl_add_u64 v[210:211], v[198:199], 0, s[16:17]
	global_load_dwordx4 v[144:147], v[198:199], off offset:0
	global_load_dwordx4 v[148:151], v[198:199], off offset:1024
	global_load_dwordx4 v[152:155], v[198:199], off offset:2048
	global_load_dwordx4 v[156:159], v[198:199], off offset:3072
	global_load_dwordx4 v[160:163], v[210:211], off offset:0
	global_load_dwordx4 v[164:167], v[210:211], off offset:1024
	global_load_dwordx4 v[180:183], v[210:211], off offset:2048
	global_load_dwordx4 v[184:187], v[210:211], off offset:3072
	v_lshlrev_b32_e32 v220, 1, v200
	v_mov_b32_e32 v221, 0
	v_lshlrev_b64 v[208:209], 13, v[196:197]
	v_lshl_add_u64 v[208:209], v[208:209], 0, v[220:221]
	v_lshl_add_u64 v[208:209], s[2:3], 0, v[208:209]
	v_lshlrev_b64 v[222:223], 8, v[196:197]
	v_lshl_add_u64 v[222:223], s[6:7], 0, v[222:223]
	s_lshl_b32 s16, s44, 2
	s_sub_i32 s16, s16, 32
	s_or_b32 s16, s16, s8
	s_lshl_b32 s16, s16, 3
	s_ashr_i32 s17, s16, 31
	v_lshl_add_u64 v[222:223], v[222:223], 0, s[16:17]
	s_mov_b64 s[42:43], 0x20000
	s_waitcnt vmcnt(0)
	v_add_f32_e32 v144, v144, v145
	v_add_f32_e32 v146, v146, v147
	v_add_f32_e32 v148, v148, v149
	v_add_f32_e32 v150, v150, v151
	v_add_f32_e32 v152, v152, v153
	v_add_f32_e32 v154, v154, v155
	v_add_f32_e32 v156, v156, v157
	v_add_f32_e32 v158, v158, v159
	v_add_f32_e32 v160, v160, v161
	v_add_f32_e32 v162, v162, v163
	v_add_f32_e32 v164, v164, v165
	v_add_f32_e32 v166, v166, v167
	v_add_f32_e32 v180, v180, v181
	v_add_f32_e32 v182, v182, v183
	v_add_f32_e32 v184, v184, v185
	v_add_f32_e32 v186, v186, v187
	v_add_f32_e32 v188, v144, v146
	v_add_f32_e32 v189, v148, v150
	v_add_f32_e32 v190, v152, v154
	v_add_f32_e32 v191, v156, v158
	v_add_f32_e32 v192, v160, v162
	v_add_f32_e32 v193, v164, v166
	v_add_f32_e32 v194, v180, v182
	v_add_f32_e32 v195, v184, v186
	v_mov_b32_e32 v144, v188
	v_mov_b32_e32 v145, v188
	v_mov_b32_e32 v148, v189
	v_mov_b32_e32 v149, v189
	v_mov_b32_e32 v152, v190
	v_mov_b32_e32 v153, v190
	v_mov_b32_e32 v156, v191
	v_mov_b32_e32 v157, v191
	v_mov_b32_e32 v160, v192
	v_mov_b32_e32 v161, v192
	v_mov_b32_e32 v164, v193
	v_mov_b32_e32 v165, v193
	v_mov_b32_e32 v180, v194
	v_mov_b32_e32 v181, v194
	v_mov_b32_e32 v184, v195
	v_mov_b32_e32 v185, v195
	s_nop 1
	v_permlane16_swap_b32_e32 v144, v145
	v_permlane16_swap_b32_e32 v148, v149
	v_permlane16_swap_b32_e32 v152, v153
	v_permlane16_swap_b32_e32 v156, v157
	v_permlane16_swap_b32_e32 v160, v161
	v_permlane16_swap_b32_e32 v164, v165
	v_permlane16_swap_b32_e32 v180, v181
	v_permlane16_swap_b32_e32 v184, v185
	v_add_f32_e32 v188, v144, v145
	v_add_f32_e32 v189, v148, v149
	v_add_f32_e32 v190, v152, v153
	v_add_f32_e32 v191, v156, v157
	v_add_f32_e32 v192, v160, v161
	v_add_f32_e32 v193, v164, v165
	v_add_f32_e32 v194, v180, v181
	v_add_f32_e32 v195, v184, v185
	v_mov_b32_e32 v144, v188
	v_mov_b32_e32 v145, v188
	v_mov_b32_e32 v148, v189
	v_mov_b32_e32 v149, v189
	v_mov_b32_e32 v152, v190
	v_mov_b32_e32 v153, v190
	v_mov_b32_e32 v156, v191
	v_mov_b32_e32 v157, v191
	v_mov_b32_e32 v160, v192
	v_mov_b32_e32 v161, v192
	v_mov_b32_e32 v164, v193
	v_mov_b32_e32 v165, v193
	v_mov_b32_e32 v180, v194
	v_mov_b32_e32 v181, v194
	v_mov_b32_e32 v184, v195
	v_mov_b32_e32 v185, v195
	s_nop 1
	v_permlane32_swap_b32_e32 v144, v145
	v_permlane32_swap_b32_e32 v148, v149
	v_permlane32_swap_b32_e32 v152, v153
	v_permlane32_swap_b32_e32 v156, v157
	v_permlane32_swap_b32_e32 v160, v161
	v_permlane32_swap_b32_e32 v164, v165
	v_permlane32_swap_b32_e32 v180, v181
	v_permlane32_swap_b32_e32 v184, v185
	v_add_f32_e32 v188, v144, v145
	v_add_f32_e32 v189, v148, v149
	v_add_f32_e32 v190, v152, v153
	v_add_f32_e32 v191, v156, v157
	v_add_f32_e32 v192, v160, v161
	v_add_f32_e32 v193, v164, v165
	v_add_f32_e32 v194, v180, v181
	v_add_f32_e32 v195, v184, v185
	v_mov_b32_e32 v206, 0x358637bd
	v_fmamk_f32 v188, v188, 0x3a800000, v206
	v_fmamk_f32 v189, v189, 0x3a800000, v206
	v_fmamk_f32 v190, v190, 0x3a800000, v206
	v_fmamk_f32 v191, v191, 0x3a800000, v206
	v_fmamk_f32 v192, v192, 0x3a800000, v206
	v_fmamk_f32 v193, v193, 0x3a800000, v206
	v_fmamk_f32 v194, v194, 0x3a800000, v206
	v_fmamk_f32 v195, v195, 0x3a800000, v206
	v_rsq_f32_e32 v144, v188
	v_rsq_f32_e32 v146, v189
	v_rsq_f32_e32 v148, v190
	v_rsq_f32_e32 v150, v191
	v_rsq_f32_e32 v152, v192
	v_rsq_f32_e32 v154, v193
	v_rsq_f32_e32 v156, v194
	v_rsq_f32_e32 v158, v195
	s_nop 0
	v_mov_b32_e32 v200, 0x3dd2d3e8
	v_mov_b32_e32 v206, 0x40135761
	v_mov_b32_e32 v196, 1.0
	s_cmp_lt_i32 s44, 8
	s_cbranch_scc1 .Lwin_epi_nostats
; __device__ __forceinline__ unsigned cvt_pk_bf16(float lo, float hi) { unsigned r; asm volatile("v_cvt_pk_bf16_f32 %0, %1, %2" : "=v"(r) : "v"(lo), "v"(hi)); return r; }
; __device__ __forceinline__ float gelu_tanh(float x) {
;     const float u = x * (0.7978845608f + 0.0356774081f * x * x);
;     const float e = __builtin_amdgcn_exp2f(u * 2.8853900818f);
;     return x - x * __builtin_amdgcn_rcpf(e + 1.0f);
; }
;     __device__ __forceinline__ void operator()(const f32x4 (&acc)[2][2][4][2], const Unit& u, int wr, int wc, int fr, int fq) const {
;     ...
;             for (int m = 0; m < 4; ++m) { const int row = row0 + ai * HALF + m * 16; bf16_t* rowp = O + (size_t)row * ldc + col0; float s = 0.f, q = 0.f;
;                 const float rstd = rsv[ai][m];
; #pragma unroll
;                 for (int bj = 0; bj < 2; ++bj) { f32x4 v0 = acc[ai][bj][m][0] * rstd + bv[bj][0], v1 = acc[ai][bj][m][1] * rstd + bv[bj][1];
;                     if (ACT == 1) {
; #pragma unroll
;                         for (int e = 0; e < 4; ++e) { const float a = fmaxf(v0[e], 0.f), b2 = fmaxf(v1[e], 0.f); v0[e] = a * a; v1[e] = b2 * b2; } }
;                     if (ACT == 2) {
; #pragma unroll
;                         for (int e = 0; e < 4; ++e) { v0[e] = gelu_tanh(v0[e]); v1[e] = gelu_tanh(v1[e]); s += v0[e] + v1[e]; q += v0[e] * v0[e] + v1[e] * v1[e]; } }
;                     u32x4 w; w.x = cvt_pk_bf16(v0[0], v0[1]); w.y = cvt_pk_bf16(v0[2], v0[3]); w.z = cvt_pk_bf16(v1[0], v1[1]); w.w = cvt_pk_bf16(v1[2], v1[3]);
;                     *(u32x4*)(rowp + bj * HALF) = w; }
;                 if (ACT == 2) { if (u.pn >= 8) { s += __shfl_xor(s, 16); s += __shfl_xor(s, 32); q += __shfl_xor(q, 16); q += __shfl_xor(q, 32);
;                     if (fq == 0) *(f32x2*)(stats + ((size_t)row * 32 + (u.pn - 8) * 4 + wc) * 2) = (f32x2){s, q}; } }
	v_pk_fma_f32 v[140:141], v[140:141], v[144:145], v[32:33] op_sel_hi:[1,0,1]
	v_pk_fma_f32 v[142:143], v[142:143], v[144:145], v[34:35] op_sel_hi:[1,0,1]
	v_pk_fma_f32 v[136:137], v[136:137], v[144:145], v[36:37] op_sel_hi:[1,0,1]
	v_pk_fma_f32 v[138:139], v[138:139], v[144:145], v[38:39] op_sel_hi:[1,0,1]
	v_pk_mul_f32 v[180:181], v[140:141], v[140:141]
	v_pk_mul_f32 v[182:183], v[142:143], v[142:143]
	v_pk_mul_f32 v[184:185], v[136:137], v[136:137]
	v_pk_mul_f32 v[186:187], v[138:139], v[138:139]
	v_pk_fma_f32 v[180:181], v[180:181], v[200:201], v[206:207] op_sel_hi:[1,0,0]
	v_pk_fma_f32 v[182:183], v[182:183], v[200:201], v[206:207] op_sel_hi:[1,0,0]
	v_pk_fma_f32 v[184:185], v[184:185], v[200:201], v[206:207] op_sel_hi:[1,0,0]
	v_pk_fma_f32 v[186:187], v[186:187], v[200:201], v[206:207] op_sel_hi:[1,0,0]
	v_pk_mul_f32 v[180:181], v[180:181], v[140:141]
	v_pk_mul_f32 v[182:183], v[182:183], v[142:143]
	v_pk_mul_f32 v[184:185], v[184:185], v[136:137]
	v_pk_mul_f32 v[186:187], v[186:187], v[138:139]
	v_exp_f32_e32 v188, v180
	v_exp_f32_e32 v189, v181
	v_exp_f32_e32 v190, v182
	v_exp_f32_e32 v191, v183
	v_exp_f32_e32 v192, v184
	v_exp_f32_e32 v193, v185
	v_exp_f32_e32 v194, v186
	v_exp_f32_e32 v195, v187
	v_pk_add_f32 v[188:189], v[188:189], v[196:197] op_sel_hi:[1,0]
	v_pk_add_f32 v[190:191], v[190:191], v[196:197] op_sel_hi:[1,0]
	v_pk_add_f32 v[192:193], v[192:193], v[196:197] op_sel_hi:[1,0]
	v_pk_add_f32 v[194:195], v[194:195], v[196:197] op_sel_hi:[1,0]
	v_rcp_f32_e32 v188, v188
	v_rcp_f32_e32 v189, v189
	v_rcp_f32_e32 v190, v190
	v_rcp_f32_e32 v191, v191
	v_rcp_f32_e32 v192, v192
	v_rcp_f32_e32 v193, v193
	v_rcp_f32_e32 v194, v194
	v_rcp_f32_e32 v195, v195
	s_nop 0
	v_pk_fma_f32 v[140:141], v[140:141], v[188:189], v[140:141] neg_lo:[1,0,0] neg_hi:[1,0,0]
	v_pk_fma_f32 v[142:143], v[142:143], v[190:191], v[142:143] neg_lo:[1,0,0] neg_hi:[1,0,0]
	v_pk_fma_f32 v[136:137], v[136:137], v[192:193], v[136:137] neg_lo:[1,0,0] neg_hi:[1,0,0]
	v_pk_fma_f32 v[138:139], v[138:139], v[194:195], v[138:139] neg_lo:[1,0,0] neg_hi:[1,0,0]
	v_pk_mul_f32 v[220:221], v[140:141], v[140:141]
	v_pk_add_f32 v[198:199], v[140:141], v[142:143]
	v_pk_fma_f32 v[220:221], v[142:143], v[142:143], v[220:221]
	v_pk_fma_f32 v[220:221], v[136:137], v[136:137], v[220:221]
	v_pk_add_f32 v[198:199], v[198:199], v[136:137]
	v_pk_fma_f32 v[220:221], v[138:139], v[138:139], v[220:221]
	v_pk_add_f32 v[198:199], v[198:199], v[138:139]
	v_cvt_pk_bf16_f32 v160, v140, v141
	v_cvt_pk_bf16_f32 v161, v142, v143
	v_cvt_pk_bf16_f32 v162, v136, v137
	v_cvt_pk_bf16_f32 v163, v138, v139
	global_store_dwordx4 v[208:209], v[160:163], off sc1
	v_pk_fma_f32 v[132:133], v[132:133], v[144:145], v[40:41] op_sel_hi:[1,0,1]
	v_pk_fma_f32 v[134:135], v[134:135], v[144:145], v[42:43] op_sel_hi:[1,0,1]
	v_pk_fma_f32 v[128:129], v[128:129], v[144:145], v[44:45] op_sel_hi:[1,0,1]
	v_pk_fma_f32 v[130:131], v[130:131], v[144:145], v[46:47] op_sel_hi:[1,0,1]
	v_pk_mul_f32 v[180:181], v[132:133], v[132:133]
	v_pk_mul_f32 v[182:183], v[134:135], v[134:135]
	v_pk_mul_f32 v[184:185], v[128:129], v[128:129]
	v_pk_mul_f32 v[186:187], v[130:131], v[130:131]
	v_pk_fma_f32 v[180:181], v[180:181], v[200:201], v[206:207] op_sel_hi:[1,0,0]
	v_pk_fma_f32 v[182:183], v[182:183], v[200:201], v[206:207] op_sel_hi:[1,0,0]
	v_pk_fma_f32 v[184:185], v[184:185], v[200:201], v[206:207] op_sel_hi:[1,0,0]
	v_pk_fma_f32 v[186:187], v[186:187], v[200:201], v[206:207] op_sel_hi:[1,0,0]
	v_pk_mul_f32 v[180:181], v[180:181], v[132:133]
	v_pk_mul_f32 v[182:183], v[182:183], v[134:135]
	v_pk_mul_f32 v[184:185], v[184:185], v[128:129]
	v_pk_mul_f32 v[186:187], v[186:187], v[130:131]
	v_exp_f32_e32 v188, v180
	v_exp_f32_e32 v189, v181
	v_exp_f32_e32 v190, v182
	v_exp_f32_e32 v191, v183
	v_exp_f32_e32 v192, v184
	v_exp_f32_e32 v193, v185
	v_exp_f32_e32 v194, v186
	v_exp_f32_e32 v195, v187
	v_pk_add_f32 v[188:189], v[188:189], v[196:197] op_sel_hi:[1,0]
	v_pk_add_f32 v[190:191], v[190:191], v[196:197] op_sel_hi:[1,0]
	v_pk_add_f32 v[192:193], v[192:193], v[196:197] op_sel_hi:[1,0]
	v_pk_add_f32 v[194:195], v[194:195], v[196:197] op_sel_hi:[1,0]
	v_rcp_f32_e32 v188, v188
	v_rcp_f32_e32 v189, v189
	v_rcp_f32_e32 v190, v190
	v_rcp_f32_e32 v191, v191
	v_rcp_f32_e32 v192, v192
	v_rcp_f32_e32 v193, v193
	v_rcp_f32_e32 v194, v194
	v_rcp_f32_e32 v195, v195
	s_nop 0
	v_pk_fma_f32 v[132:133], v[132:133], v[188:189], v[132:133] neg_lo:[1,0,0] neg_hi:[1,0,0]
	v_pk_fma_f32 v[134:135], v[134:135], v[190:191], v[134:135] neg_lo:[1,0,0] neg_hi:[1,0,0]
	v_pk_fma_f32 v[128:129], v[128:129], v[192:193], v[128:129] neg_lo:[1,0,0] neg_hi:[1,0,0]
	v_pk_fma_f32 v[130:131], v[130:131], v[194:195], v[130:131] neg_lo:[1,0,0] neg_hi:[1,0,0]
	v_pk_fma_f32 v[220:221], v[132:133], v[132:133], v[220:221]
	v_pk_add_f32 v[198:199], v[198:199], v[132:133]
	v_pk_fma_f32 v[220:221], v[134:135], v[134:135], v[220:221]
	v_pk_add_f32 v[198:199], v[198:199], v[134:135]
	v_pk_fma_f32 v[220:221], v[128:129], v[128:129], v[220:221]
	v_pk_add_f32 v[198:199], v[198:199], v[128:129]
	v_pk_fma_f32 v[220:221], v[130:131], v[130:131], v[220:221]
	v_pk_add_f32 v[198:199], v[198:199], v[130:131]
	v_cvt_pk_bf16_f32 v164, v132, v133
	v_cvt_pk_bf16_f32 v165, v134, v135
	v_cvt_pk_bf16_f32 v166, v128, v129
	v_cvt_pk_bf16_f32 v167, v130, v131
	global_store_dwordx4 v[208:209], v[164:167], off offset:256 sc1
	v_add_f32_e32 v210, v198, v199
	v_add_f32_e32 v211, v220, v221
	v_mov_b32_e32 v198, v210
	v_mov_b32_e32 v199, v210
	v_mov_b32_e32 v220, v211
	v_mov_b32_e32 v221, v211
	s_nop 1
	v_permlane16_swap_b32_e32 v198, v199
	v_permlane16_swap_b32_e32 v220, v221
	v_add_f32_e32 v210, v198, v199
; __device__ __forceinline__ unsigned cvt_pk_bf16(float lo, float hi) { unsigned r; asm volatile("v_cvt_pk_bf16_f32 %0, %1, %2" : "=v"(r) : "v"(lo), "v"(hi)); return r; }
; __device__ __forceinline__ float gelu_tanh(float x) {
;     const float u = x * (0.7978845608f + 0.0356774081f * x * x);
;     const float e = __builtin_amdgcn_exp2f(u * 2.8853900818f);
;     return x - x * __builtin_amdgcn_rcpf(e + 1.0f);
; }
;     __device__ __forceinline__ void operator()(const f32x4 (&acc)[2][2][4][2], const Unit& u, int wr, int wc, int fr, int fq) const {
;     ...
;             for (int m = 0; m < 4; ++m) { const int row = row0 + ai * HALF + m * 16; bf16_t* rowp = O + (size_t)row * ldc + col0; float s = 0.f, q = 0.f;
;                 const float rstd = rsv[ai][m];
; #pragma unroll
;                 for (int bj = 0; bj < 2; ++bj) { f32x4 v0 = acc[ai][bj][m][0] * rstd + bv[bj][0], v1 = acc[ai][bj][m][1] * rstd + bv[bj][1];
;                     if (ACT == 1) {
; #pragma unroll
;                         for (int e = 0; e < 4; ++e) { const float a = fmaxf(v0[e], 0.f), b2 = fmaxf(v1[e], 0.f); v0[e] = a * a; v1[e] = b2 * b2; } }
;                     if (ACT == 2) {
; #pragma unroll
;                         for (int e = 0; e < 4; ++e) { v0[e] = gelu_tanh(v0[e]); v1[e] = gelu_tanh(v1[e]); s += v0[e] + v1[e]; q += v0[e] * v0[e] + v1[e] * v1[e]; } }
;                     u32x4 w; w.x = cvt_pk_bf16(v0[0], v0[1]); w.y = cvt_pk_bf16(v0[2], v0[3]); w.z = cvt_pk_bf16(v1[0], v1[1]); w.w = cvt_pk_bf16(v1[2], v1[3]);
;                     *(u32x4*)(rowp + bj * HALF) = w; }
;                 if (ACT == 2) { if (u.pn >= 8) { s += __shfl_xor(s, 16); s += __shfl_xor(s, 32); q += __shfl_xor(q, 16); q += __shfl_xor(q, 32);
;                     if (fq == 0) *(f32x2*)(stats + ((size_t)row * 32 + (u.pn - 8) * 4 + wc) * 2) = (f32x2){s, q}; } }
	v_add_f32_e32 v211, v220, v221
	v_mov_b32_e32 v198, v210
	v_mov_b32_e32 v199, v210
	v_mov_b32_e32 v220, v211
	v_mov_b32_e32 v221, v211
	s_nop 1
	v_permlane32_swap_b32_e32 v198, v199
	v_permlane32_swap_b32_e32 v220, v221
	v_add_f32_e32 v210, v198, v199
	v_add_f32_e32 v211, v220, v221
	s_and_saveexec_b64 s[16:17], s[38:39]
	global_store_dwordx2 v[222:223], v[210:211], off
	s_or_b64 exec, exec, s[16:17]
	s_mov_b64 s[16:17], 0x1000
	v_lshl_add_u64 v[222:223], v[222:223], 0, s[16:17]
	v_pk_fma_f32 v[124:125], v[124:125], v[146:147], v[32:33] op_sel_hi:[1,0,1]
	v_pk_fma_f32 v[126:127], v[126:127], v[146:147], v[34:35] op_sel_hi:[1,0,1]
	v_pk_fma_f32 v[120:121], v[120:121], v[146:147], v[36:37] op_sel_hi:[1,0,1]
	v_pk_fma_f32 v[122:123], v[122:123], v[146:147], v[38:39] op_sel_hi:[1,0,1]
	v_lshl_add_u64 v[208:209], v[208:209], 0, s[42:43]
	v_pk_mul_f32 v[180:181], v[124:125], v[124:125]
	v_pk_mul_f32 v[182:183], v[126:127], v[126:127]
	v_pk_mul_f32 v[184:185], v[120:121], v[120:121]
	v_pk_mul_f32 v[186:187], v[122:123], v[122:123]
	v_pk_fma_f32 v[180:181], v[180:181], v[200:201], v[206:207] op_sel_hi:[1,0,0]
	v_pk_fma_f32 v[182:183], v[182:183], v[200:201], v[206:207] op_sel_hi:[1,0,0]
	v_pk_fma_f32 v[184:185], v[184:185], v[200:201], v[206:207] op_sel_hi:[1,0,0]
	v_pk_fma_f32 v[186:187], v[186:187], v[200:201], v[206:207] op_sel_hi:[1,0,0]
	v_pk_mul_f32 v[180:181], v[180:181], v[124:125]
	v_pk_mul_f32 v[182:183], v[182:183], v[126:127]
	v_pk_mul_f32 v[184:185], v[184:185], v[120:121]
	v_pk_mul_f32 v[186:187], v[186:187], v[122:123]
	v_exp_f32_e32 v188, v180
	v_exp_f32_e32 v189, v181
	v_exp_f32_e32 v190, v182
	v_exp_f32_e32 v191, v183
	v_exp_f32_e32 v192, v184
	v_exp_f32_e32 v193, v185
	v_exp_f32_e32 v194, v186
	v_exp_f32_e32 v195, v187
	v_pk_add_f32 v[188:189], v[188:189], v[196:197] op_sel_hi:[1,0]
	v_pk_add_f32 v[190:191], v[190:191], v[196:197] op_sel_hi:[1,0]
	v_pk_add_f32 v[192:193], v[192:193], v[196:197] op_sel_hi:[1,0]
	v_pk_add_f32 v[194:195], v[194:195], v[196:197] op_sel_hi:[1,0]
	v_rcp_f32_e32 v188, v188
	v_rcp_f32_e32 v189, v189
	v_rcp_f32_e32 v190, v190
	v_rcp_f32_e32 v191, v191
	v_rcp_f32_e32 v192, v192
	v_rcp_f32_e32 v193, v193
	v_rcp_f32_e32 v194, v194
	v_rcp_f32_e32 v195, v195
	s_nop 0
	v_pk_fma_f32 v[124:125], v[124:125], v[188:189], v[124:125] neg_lo:[1,0,0] neg_hi:[1,0,0]
	v_pk_fma_f32 v[126:127], v[126:127], v[190:191], v[126:127] neg_lo:[1,0,0] neg_hi:[1,0,0]
	v_pk_fma_f32 v[120:121], v[120:121], v[192:193], v[120:121] neg_lo:[1,0,0] neg_hi:[1,0,0]
	v_pk_fma_f32 v[122:123], v[122:123], v[194:195], v[122:123] neg_lo:[1,0,0] neg_hi:[1,0,0]
	v_pk_mul_f32 v[220:221], v[124:125], v[124:125]
	v_pk_add_f32 v[198:199], v[124:125], v[126:127]
	v_pk_fma_f32 v[220:221], v[126:127], v[126:127], v[220:221]
	v_pk_fma_f32 v[220:221], v[120:121], v[120:121], v[220:221]
	v_pk_add_f32 v[198:199], v[198:199], v[120:121]
	v_pk_fma_f32 v[220:221], v[122:123], v[122:123], v[220:221]
	v_pk_add_f32 v[198:199], v[198:199], v[122:123]
	v_cvt_pk_bf16_f32 v160, v124, v125
	v_cvt_pk_bf16_f32 v161, v126, v127
	v_cvt_pk_bf16_f32 v162, v120, v121
	v_cvt_pk_bf16_f32 v163, v122, v123
	global_store_dwordx4 v[208:209], v[160:163], off sc1
	v_pk_fma_f32 v[116:117], v[116:117], v[146:147], v[40:41] op_sel_hi:[1,0,1]
	v_pk_fma_f32 v[118:119], v[118:119], v[146:147], v[42:43] op_sel_hi:[1,0,1]
	v_pk_fma_f32 v[112:113], v[112:113], v[146:147], v[44:45] op_sel_hi:[1,0,1]
	v_pk_fma_f32 v[114:115], v[114:115], v[146:147], v[46:47] op_sel_hi:[1,0,1]
	v_pk_mul_f32 v[180:181], v[116:117], v[116:117]
	v_pk_mul_f32 v[182:183], v[118:119], v[118:119]
	v_pk_mul_f32 v[184:185], v[112:113], v[112:113]
	v_pk_mul_f32 v[186:187], v[114:115], v[114:115]
	v_pk_fma_f32 v[180:181], v[180:181], v[200:201], v[206:207] op_sel_hi:[1,0,0]
	v_pk_fma_f32 v[182:183], v[182:183], v[200:201], v[206:207] op_sel_hi:[1,0,0]
	v_pk_fma_f32 v[184:185], v[184:185], v[200:201], v[206:207] op_sel_hi:[1,0,0]
	v_pk_fma_f32 v[186:187], v[186:187], v[200:201], v[206:207] op_sel_hi:[1,0,0]
	v_pk_mul_f32 v[180:181], v[180:181], v[116:117]
	v_pk_mul_f32 v[182:183], v[182:183], v[118:119]
	v_pk_mul_f32 v[184:185], v[184:185], v[112:113]
	v_pk_mul_f32 v[186:187], v[186:187], v[114:115]
	v_exp_f32_e32 v188, v180
	v_exp_f32_e32 v189, v181
	v_exp_f32_e32 v190, v182
	v_exp_f32_e32 v191, v183
	v_exp_f32_e32 v192, v184
	v_exp_f32_e32 v193, v185
	v_exp_f32_e32 v194, v186
	v_exp_f32_e32 v195, v187
	v_pk_add_f32 v[188:189], v[188:189], v[196:197] op_sel_hi:[1,0]
	v_pk_add_f32 v[190:191], v[190:191], v[196:197] op_sel_hi:[1,0]
	v_pk_add_f32 v[192:193], v[192:193], v[196:197] op_sel_hi:[1,0]
	v_pk_add_f32 v[194:195], v[194:195], v[196:197] op_sel_hi:[1,0]
	v_rcp_f32_e32 v188, v188
	v_rcp_f32_e32 v189, v189
	v_rcp_f32_e32 v190, v190
	v_rcp_f32_e32 v191, v191
	v_rcp_f32_e32 v192, v192
	v_rcp_f32_e32 v193, v193
	v_rcp_f32_e32 v194, v194
	v_rcp_f32_e32 v195, v195
	s_nop 0
	v_pk_fma_f32 v[116:117], v[116:117], v[188:189], v[116:117] neg_lo:[1,0,0] neg_hi:[1,0,0]
	v_pk_fma_f32 v[118:119], v[118:119], v[190:191], v[118:119] neg_lo:[1,0,0] neg_hi:[1,0,0]
	v_pk_fma_f32 v[112:113], v[112:113], v[192:193], v[112:113] neg_lo:[1,0,0] neg_hi:[1,0,0]
	v_pk_fma_f32 v[114:115], v[114:115], v[194:195], v[114:115] neg_lo:[1,0,0] neg_hi:[1,0,0]
	v_pk_fma_f32 v[220:221], v[116:117], v[116:117], v[220:221]
	v_pk_add_f32 v[198:199], v[198:199], v[116:117]
	v_pk_fma_f32 v[220:221], v[118:119], v[118:119], v[220:221]
	v_pk_add_f32 v[198:199], v[198:199], v[118:119]
	v_pk_fma_f32 v[220:221], v[112:113], v[112:113], v[220:221]
	v_pk_add_f32 v[198:199], v[198:199], v[112:113]
	v_pk_fma_f32 v[220:221], v[114:115], v[114:115], v[220:221]
; __device__ __forceinline__ unsigned cvt_pk_bf16(float lo, float hi) { unsigned r; asm volatile("v_cvt_pk_bf16_f32 %0, %1, %2" : "=v"(r) : "v"(lo), "v"(hi)); return r; }
; __device__ __forceinline__ float gelu_tanh(float x) {
;     const float u = x * (0.7978845608f + 0.0356774081f * x * x);
;     const float e = __builtin_amdgcn_exp2f(u * 2.8853900818f);
;     return x - x * __builtin_amdgcn_rcpf(e + 1.0f);
; }
;     __device__ __forceinline__ void operator()(const f32x4 (&acc)[2][2][4][2], const Unit& u, int wr, int wc, int fr, int fq) const {
;     ...
;             for (int m = 0; m < 4; ++m) { const int row = row0 + ai * HALF + m * 16; bf16_t* rowp = O + (size_t)row * ldc + col0; float s = 0.f, q = 0.f;
;                 const float rstd = rsv[ai][m];
; #pragma unroll
;                 for (int bj = 0; bj < 2; ++bj) { f32x4 v0 = acc[ai][bj][m][0] * rstd + bv[bj][0], v1 = acc[ai][bj][m][1] * rstd + bv[bj][1];
;                     if (ACT == 1) {
; #pragma unroll
;                         for (int e = 0; e < 4; ++e) { const float a = fmaxf(v0[e], 0.f), b2 = fmaxf(v1[e], 0.f); v0[e] = a * a; v1[e] = b2 * b2; } }
;                     if (ACT == 2) {
; #pragma unroll
;                         for (int e = 0; e < 4; ++e) { v0[e] = gelu_tanh(v0[e]); v1[e] = gelu_tanh(v1[e]); s += v0[e] + v1[e]; q += v0[e] * v0[e] + v1[e] * v1[e]; } }
;                     u32x4 w; w.x = cvt_pk_bf16(v0[0], v0[1]); w.y = cvt_pk_bf16(v0[2], v0[3]); w.z = cvt_pk_bf16(v1[0], v1[1]); w.w = cvt_pk_bf16(v1[2], v1[3]);
;                     *(u32x4*)(rowp + bj * HALF) = w; }
;                 if (ACT == 2) { if (u.pn >= 8) { s += __shfl_xor(s, 16); s += __shfl_xor(s, 32); q += __shfl_xor(q, 16); q += __shfl_xor(q, 32);
;                     if (fq == 0) *(f32x2*)(stats + ((size_t)row * 32 + (u.pn - 8) * 4 + wc) * 2) = (f32x2){s, q}; } }
	v_pk_add_f32 v[198:199], v[198:199], v[114:115]
	v_cvt_pk_bf16_f32 v164, v116, v117
	v_cvt_pk_bf16_f32 v165, v118, v119
	v_cvt_pk_bf16_f32 v166, v112, v113
	v_cvt_pk_bf16_f32 v167, v114, v115
	global_store_dwordx4 v[208:209], v[164:167], off offset:256 sc1
	v_add_f32_e32 v210, v198, v199
	v_add_f32_e32 v211, v220, v221
	v_mov_b32_e32 v198, v210
	v_mov_b32_e32 v199, v210
	v_mov_b32_e32 v220, v211
	v_mov_b32_e32 v221, v211
	s_nop 1
	v_permlane16_swap_b32_e32 v198, v199
	v_permlane16_swap_b32_e32 v220, v221
	v_add_f32_e32 v210, v198, v199
	v_add_f32_e32 v211, v220, v221
	v_mov_b32_e32 v198, v210
	v_mov_b32_e32 v199, v210
	v_mov_b32_e32 v220, v211
	v_mov_b32_e32 v221, v211
	s_nop 1
	v_permlane32_swap_b32_e32 v198, v199
	v_permlane32_swap_b32_e32 v220, v221
	v_add_f32_e32 v210, v198, v199
	v_add_f32_e32 v211, v220, v221
	s_and_saveexec_b64 s[16:17], s[38:39]
	global_store_dwordx2 v[222:223], v[210:211], off
	s_or_b64 exec, exec, s[16:17]
	s_mov_b64 s[16:17], 0x1000
	v_lshl_add_u64 v[222:223], v[222:223], 0, s[16:17]
	v_pk_fma_f32 v[108:109], v[108:109], v[148:149], v[32:33] op_sel_hi:[1,0,1]
	v_pk_fma_f32 v[110:111], v[110:111], v[148:149], v[34:35] op_sel_hi:[1,0,1]
	v_pk_fma_f32 v[104:105], v[104:105], v[148:149], v[36:37] op_sel_hi:[1,0,1]
	v_pk_fma_f32 v[106:107], v[106:107], v[148:149], v[38:39] op_sel_hi:[1,0,1]
	v_lshl_add_u64 v[208:209], v[208:209], 0, s[42:43]
	v_pk_mul_f32 v[180:181], v[108:109], v[108:109]
	v_pk_mul_f32 v[182:183], v[110:111], v[110:111]
	v_pk_mul_f32 v[184:185], v[104:105], v[104:105]
	v_pk_mul_f32 v[186:187], v[106:107], v[106:107]
	v_pk_fma_f32 v[180:181], v[180:181], v[200:201], v[206:207] op_sel_hi:[1,0,0]
	v_pk_fma_f32 v[182:183], v[182:183], v[200:201], v[206:207] op_sel_hi:[1,0,0]
	v_pk_fma_f32 v[184:185], v[184:185], v[200:201], v[206:207] op_sel_hi:[1,0,0]
	v_pk_fma_f32 v[186:187], v[186:187], v[200:201], v[206:207] op_sel_hi:[1,0,0]
	v_pk_mul_f32 v[180:181], v[180:181], v[108:109]
	v_pk_mul_f32 v[182:183], v[182:183], v[110:111]
	v_pk_mul_f32 v[184:185], v[184:185], v[104:105]
	v_pk_mul_f32 v[186:187], v[186:187], v[106:107]
	v_exp_f32_e32 v188, v180
	v_exp_f32_e32 v189, v181
	v_exp_f32_e32 v190, v182
	v_exp_f32_e32 v191, v183
	v_exp_f32_e32 v192, v184
	v_exp_f32_e32 v193, v185
	v_exp_f32_e32 v194, v186
	v_exp_f32_e32 v195, v187
	v_pk_add_f32 v[188:189], v[188:189], v[196:197] op_sel_hi:[1,0]
	v_pk_add_f32 v[190:191], v[190:191], v[196:197] op_sel_hi:[1,0]
	v_pk_add_f32 v[192:193], v[192:193], v[196:197] op_sel_hi:[1,0]
	v_pk_add_f32 v[194:195], v[194:195], v[196:197] op_sel_hi:[1,0]
	v_rcp_f32_e32 v188, v188
	v_rcp_f32_e32 v189, v189
	v_rcp_f32_e32 v190, v190
	v_rcp_f32_e32 v191, v191
	v_rcp_f32_e32 v192, v192
	v_rcp_f32_e32 v193, v193
	v_rcp_f32_e32 v194, v194
	v_rcp_f32_e32 v195, v195
	s_nop 0
	v_pk_fma_f32 v[108:109], v[108:109], v[188:189], v[108:109] neg_lo:[1,0,0] neg_hi:[1,0,0]
	v_pk_fma_f32 v[110:111], v[110:111], v[190:191], v[110:111] neg_lo:[1,0,0] neg_hi:[1,0,0]
	v_pk_fma_f32 v[104:105], v[104:105], v[192:193], v[104:105] neg_lo:[1,0,0] neg_hi:[1,0,0]
	v_pk_fma_f32 v[106:107], v[106:107], v[194:195], v[106:107] neg_lo:[1,0,0] neg_hi:[1,0,0]
	v_pk_mul_f32 v[220:221], v[108:109], v[108:109]
	v_pk_add_f32 v[198:199], v[108:109], v[110:111]
	v_pk_fma_f32 v[220:221], v[110:111], v[110:111], v[220:221]
	v_pk_fma_f32 v[220:221], v[104:105], v[104:105], v[220:221]
	v_pk_add_f32 v[198:199], v[198:199], v[104:105]
	v_pk_fma_f32 v[220:221], v[106:107], v[106:107], v[220:221]
	v_pk_add_f32 v[198:199], v[198:199], v[106:107]
	v_cvt_pk_bf16_f32 v160, v108, v109
	v_cvt_pk_bf16_f32 v161, v110, v111
	v_cvt_pk_bf16_f32 v162, v104, v105
	v_cvt_pk_bf16_f32 v163, v106, v107
	global_store_dwordx4 v[208:209], v[160:163], off sc1
	v_pk_fma_f32 v[100:101], v[100:101], v[148:149], v[40:41] op_sel_hi:[1,0,1]
	v_pk_fma_f32 v[102:103], v[102:103], v[148:149], v[42:43] op_sel_hi:[1,0,1]
	v_pk_fma_f32 v[96:97], v[96:97], v[148:149], v[44:45] op_sel_hi:[1,0,1]
	v_pk_fma_f32 v[98:99], v[98:99], v[148:149], v[46:47] op_sel_hi:[1,0,1]
	v_pk_mul_f32 v[180:181], v[100:101], v[100:101]
	v_pk_mul_f32 v[182:183], v[102:103], v[102:103]
	v_pk_mul_f32 v[184:185], v[96:97], v[96:97]
	v_pk_mul_f32 v[186:187], v[98:99], v[98:99]
	v_pk_fma_f32 v[180:181], v[180:181], v[200:201], v[206:207] op_sel_hi:[1,0,0]
	v_pk_fma_f32 v[182:183], v[182:183], v[200:201], v[206:207] op_sel_hi:[1,0,0]
	v_pk_fma_f32 v[184:185], v[184:185], v[200:201], v[206:207] op_sel_hi:[1,0,0]
	v_pk_fma_f32 v[186:187], v[186:187], v[200:201], v[206:207] op_sel_hi:[1,0,0]
	v_pk_mul_f32 v[180:181], v[180:181], v[100:101]
	v_pk_mul_f32 v[182:183], v[182:183], v[102:103]
	v_pk_mul_f32 v[184:185], v[184:185], v[96:97]
	v_pk_mul_f32 v[186:187], v[186:187], v[98:99]
	v_exp_f32_e32 v188, v180
	v_exp_f32_e32 v189, v181
	v_exp_f32_e32 v190, v182
	v_exp_f32_e32 v191, v183
	v_exp_f32_e32 v192, v184
	v_exp_f32_e32 v193, v185
	v_exp_f32_e32 v194, v186
	v_exp_f32_e32 v195, v187
	v_pk_add_f32 v[188:189], v[188:189], v[196:197] op_sel_hi:[1,0]
	v_pk_add_f32 v[190:191], v[190:191], v[196:197] op_sel_hi:[1,0]
	v_pk_add_f32 v[192:193], v[192:193], v[196:197] op_sel_hi:[1,0]
	v_pk_add_f32 v[194:195], v[194:195], v[196:197] op_sel_hi:[1,0]
	v_rcp_f32_e32 v188, v188
	v_rcp_f32_e32 v189, v189
	v_rcp_f32_e32 v190, v190
	v_rcp_f32_e32 v191, v191
	v_rcp_f32_e32 v192, v192
	v_rcp_f32_e32 v193, v193
	v_rcp_f32_e32 v194, v194
	v_rcp_f32_e32 v195, v195
	s_nop 0
	v_pk_fma_f32 v[100:101], v[100:101], v[188:189], v[100:101] neg_lo:[1,0,0] neg_hi:[1,0,0]
	v_pk_fma_f32 v[102:103], v[102:103], v[190:191], v[102:103] neg_lo:[1,0,0] neg_hi:[1,0,0]
	v_pk_fma_f32 v[96:97], v[96:97], v[192:193], v[96:97] neg_lo:[1,0,0] neg_hi:[1,0,0]
; __device__ __forceinline__ unsigned cvt_pk_bf16(float lo, float hi) { unsigned r; asm volatile("v_cvt_pk_bf16_f32 %0, %1, %2" : "=v"(r) : "v"(lo), "v"(hi)); return r; }
; __device__ __forceinline__ float gelu_tanh(float x) {
;     const float u = x * (0.7978845608f + 0.0356774081f * x * x);
;     const float e = __builtin_amdgcn_exp2f(u * 2.8853900818f);
;     return x - x * __builtin_amdgcn_rcpf(e + 1.0f);
; }
;     __device__ __forceinline__ void operator()(const f32x4 (&acc)[2][2][4][2], const Unit& u, int wr, int wc, int fr, int fq) const {
;     ...
;             for (int m = 0; m < 4; ++m) { const int row = row0 + ai * HALF + m * 16; bf16_t* rowp = O + (size_t)row * ldc + col0; float s = 0.f, q = 0.f;
;                 const float rstd = rsv[ai][m];
; #pragma unroll
;                 for (int bj = 0; bj < 2; ++bj) { f32x4 v0 = acc[ai][bj][m][0] * rstd + bv[bj][0], v1 = acc[ai][bj][m][1] * rstd + bv[bj][1];
;                     if (ACT == 1) {
; #pragma unroll
;                         for (int e = 0; e < 4; ++e) { const float a = fmaxf(v0[e], 0.f), b2 = fmaxf(v1[e], 0.f); v0[e] = a * a; v1[e] = b2 * b2; } }
;                     if (ACT == 2) {
; #pragma unroll
;                         for (int e = 0; e < 4; ++e) { v0[e] = gelu_tanh(v0[e]); v1[e] = gelu_tanh(v1[e]); s += v0[e] + v1[e]; q += v0[e] * v0[e] + v1[e] * v1[e]; } }
;                     u32x4 w; w.x = cvt_pk_bf16(v0[0], v0[1]); w.y = cvt_pk_bf16(v0[2], v0[3]); w.z = cvt_pk_bf16(v1[0], v1[1]); w.w = cvt_pk_bf16(v1[2], v1[3]);
;                     *(u32x4*)(rowp + bj * HALF) = w; }
;                 if (ACT == 2) { if (u.pn >= 8) { s += __shfl_xor(s, 16); s += __shfl_xor(s, 32); q += __shfl_xor(q, 16); q += __shfl_xor(q, 32);
;                     if (fq == 0) *(f32x2*)(stats + ((size_t)row * 32 + (u.pn - 8) * 4 + wc) * 2) = (f32x2){s, q}; } }
	v_pk_fma_f32 v[98:99], v[98:99], v[194:195], v[98:99] neg_lo:[1,0,0] neg_hi:[1,0,0]
	v_pk_fma_f32 v[220:221], v[100:101], v[100:101], v[220:221]
	v_pk_add_f32 v[198:199], v[198:199], v[100:101]
	v_pk_fma_f32 v[220:221], v[102:103], v[102:103], v[220:221]
	v_pk_add_f32 v[198:199], v[198:199], v[102:103]
	v_pk_fma_f32 v[220:221], v[96:97], v[96:97], v[220:221]
	v_pk_add_f32 v[198:199], v[198:199], v[96:97]
	v_pk_fma_f32 v[220:221], v[98:99], v[98:99], v[220:221]
	v_pk_add_f32 v[198:199], v[198:199], v[98:99]
	v_cvt_pk_bf16_f32 v164, v100, v101
	v_cvt_pk_bf16_f32 v165, v102, v103
	v_cvt_pk_bf16_f32 v166, v96, v97
	v_cvt_pk_bf16_f32 v167, v98, v99
	global_store_dwordx4 v[208:209], v[164:167], off offset:256 sc1
	v_add_f32_e32 v210, v198, v199
	v_add_f32_e32 v211, v220, v221
	v_mov_b32_e32 v198, v210
	v_mov_b32_e32 v199, v210
	v_mov_b32_e32 v220, v211
	v_mov_b32_e32 v221, v211
	s_nop 1
	v_permlane16_swap_b32_e32 v198, v199
	v_permlane16_swap_b32_e32 v220, v221
	v_add_f32_e32 v210, v198, v199
	v_add_f32_e32 v211, v220, v221
	v_mov_b32_e32 v198, v210
	v_mov_b32_e32 v199, v210
	v_mov_b32_e32 v220, v211
	v_mov_b32_e32 v221, v211
	s_nop 1
	v_permlane32_swap_b32_e32 v198, v199
	v_permlane32_swap_b32_e32 v220, v221
	v_add_f32_e32 v210, v198, v199
	v_add_f32_e32 v211, v220, v221
	s_and_saveexec_b64 s[16:17], s[38:39]
	global_store_dwordx2 v[222:223], v[210:211], off
	s_or_b64 exec, exec, s[16:17]
	s_mov_b64 s[16:17], 0x1000
	v_lshl_add_u64 v[222:223], v[222:223], 0, s[16:17]
	v_pk_fma_f32 v[92:93], v[92:93], v[150:151], v[32:33] op_sel_hi:[1,0,1]
	v_pk_fma_f32 v[94:95], v[94:95], v[150:151], v[34:35] op_sel_hi:[1,0,1]
	v_pk_fma_f32 v[88:89], v[88:89], v[150:151], v[36:37] op_sel_hi:[1,0,1]
	v_pk_fma_f32 v[90:91], v[90:91], v[150:151], v[38:39] op_sel_hi:[1,0,1]
	v_lshl_add_u64 v[208:209], v[208:209], 0, s[42:43]
	v_pk_mul_f32 v[180:181], v[92:93], v[92:93]
	v_pk_mul_f32 v[182:183], v[94:95], v[94:95]
	v_pk_mul_f32 v[184:185], v[88:89], v[88:89]
	v_pk_mul_f32 v[186:187], v[90:91], v[90:91]
	v_pk_fma_f32 v[180:181], v[180:181], v[200:201], v[206:207] op_sel_hi:[1,0,0]
	v_pk_fma_f32 v[182:183], v[182:183], v[200:201], v[206:207] op_sel_hi:[1,0,0]
	v_pk_fma_f32 v[184:185], v[184:185], v[200:201], v[206:207] op_sel_hi:[1,0,0]
	v_pk_fma_f32 v[186:187], v[186:187], v[200:201], v[206:207] op_sel_hi:[1,0,0]
	v_pk_mul_f32 v[180:181], v[180:181], v[92:93]
	v_pk_mul_f32 v[182:183], v[182:183], v[94:95]
	v_pk_mul_f32 v[184:185], v[184:185], v[88:89]
	v_pk_mul_f32 v[186:187], v[186:187], v[90:91]
	v_exp_f32_e32 v188, v180
	v_exp_f32_e32 v189, v181
	v_exp_f32_e32 v190, v182
	v_exp_f32_e32 v191, v183
	v_exp_f32_e32 v192, v184
	v_exp_f32_e32 v193, v185
	v_exp_f32_e32 v194, v186
	v_exp_f32_e32 v195, v187
	v_pk_add_f32 v[188:189], v[188:189], v[196:197] op_sel_hi:[1,0]
	v_pk_add_f32 v[190:191], v[190:191], v[196:197] op_sel_hi:[1,0]
	v_pk_add_f32 v[192:193], v[192:193], v[196:197] op_sel_hi:[1,0]
	v_pk_add_f32 v[194:195], v[194:195], v[196:197] op_sel_hi:[1,0]
	v_rcp_f32_e32 v188, v188
	v_rcp_f32_e32 v189, v189
	v_rcp_f32_e32 v190, v190
	v_rcp_f32_e32 v191, v191
	v_rcp_f32_e32 v192, v192
	v_rcp_f32_e32 v193, v193
	v_rcp_f32_e32 v194, v194
	v_rcp_f32_e32 v195, v195
	s_nop 0
	v_pk_fma_f32 v[92:93], v[92:93], v[188:189], v[92:93] neg_lo:[1,0,0] neg_hi:[1,0,0]
	v_pk_fma_f32 v[94:95], v[94:95], v[190:191], v[94:95] neg_lo:[1,0,0] neg_hi:[1,0,0]
	v_pk_fma_f32 v[88:89], v[88:89], v[192:193], v[88:89] neg_lo:[1,0,0] neg_hi:[1,0,0]
	v_pk_fma_f32 v[90:91], v[90:91], v[194:195], v[90:91] neg_lo:[1,0,0] neg_hi:[1,0,0]
	v_pk_mul_f32 v[220:221], v[92:93], v[92:93]
	v_pk_add_f32 v[198:199], v[92:93], v[94:95]
	v_pk_fma_f32 v[220:221], v[94:95], v[94:95], v[220:221]
	v_pk_fma_f32 v[220:221], v[88:89], v[88:89], v[220:221]
	v_pk_add_f32 v[198:199], v[198:199], v[88:89]
	v_pk_fma_f32 v[220:221], v[90:91], v[90:91], v[220:221]
	v_pk_add_f32 v[198:199], v[198:199], v[90:91]
	v_cvt_pk_bf16_f32 v160, v92, v93
	v_cvt_pk_bf16_f32 v161, v94, v95
	v_cvt_pk_bf16_f32 v162, v88, v89
	v_cvt_pk_bf16_f32 v163, v90, v91
	global_store_dwordx4 v[208:209], v[160:163], off sc1
	v_pk_fma_f32 v[84:85], v[84:85], v[150:151], v[40:41] op_sel_hi:[1,0,1]
	v_pk_fma_f32 v[86:87], v[86:87], v[150:151], v[42:43] op_sel_hi:[1,0,1]
	v_pk_fma_f32 v[80:81], v[80:81], v[150:151], v[44:45] op_sel_hi:[1,0,1]
	v_pk_fma_f32 v[82:83], v[82:83], v[150:151], v[46:47] op_sel_hi:[1,0,1]
	v_pk_mul_f32 v[180:181], v[84:85], v[84:85]
	v_pk_mul_f32 v[182:183], v[86:87], v[86:87]
	v_pk_mul_f32 v[184:185], v[80:81], v[80:81]
	v_pk_mul_f32 v[186:187], v[82:83], v[82:83]
	v_pk_fma_f32 v[180:181], v[180:181], v[200:201], v[206:207] op_sel_hi:[1,0,0]
	v_pk_fma_f32 v[182:183], v[182:183], v[200:201], v[206:207] op_sel_hi:[1,0,0]
	v_pk_fma_f32 v[184:185], v[184:185], v[200:201], v[206:207] op_sel_hi:[1,0,0]
	v_pk_fma_f32 v[186:187], v[186:187], v[200:201], v[206:207] op_sel_hi:[1,0,0]
	v_pk_mul_f32 v[180:181], v[180:181], v[84:85]
	v_pk_mul_f32 v[182:183], v[182:183], v[86:87]
	v_pk_mul_f32 v[184:185], v[184:185], v[80:81]
	v_pk_mul_f32 v[186:187], v[186:187], v[82:83]
	v_exp_f32_e32 v188, v180
	v_exp_f32_e32 v189, v181
	v_exp_f32_e32 v190, v182
	v_exp_f32_e32 v191, v183
	v_exp_f32_e32 v192, v184
	v_exp_f32_e32 v193, v185
	v_exp_f32_e32 v194, v186
	v_exp_f32_e32 v195, v187
	v_pk_add_f32 v[188:189], v[188:189], v[196:197] op_sel_hi:[1,0]
	v_pk_add_f32 v[190:191], v[190:191], v[196:197] op_sel_hi:[1,0]
	v_pk_add_f32 v[192:193], v[192:193], v[196:197] op_sel_hi:[1,0]
	v_pk_add_f32 v[194:195], v[194:195], v[196:197] op_sel_hi:[1,0]
	v_rcp_f32_e32 v188, v188
	v_rcp_f32_e32 v189, v189
	v_rcp_f32_e32 v190, v190
	v_rcp_f32_e32 v191, v191
; __device__ __forceinline__ unsigned cvt_pk_bf16(float lo, float hi) { unsigned r; asm volatile("v_cvt_pk_bf16_f32 %0, %1, %2" : "=v"(r) : "v"(lo), "v"(hi)); return r; }
; __device__ __forceinline__ float gelu_tanh(float x) {
;     const float u = x * (0.7978845608f + 0.0356774081f * x * x);
;     const float e = __builtin_amdgcn_exp2f(u * 2.8853900818f);
;     return x - x * __builtin_amdgcn_rcpf(e + 1.0f);
; }
;     __device__ __forceinline__ void operator()(const f32x4 (&acc)[2][2][4][2], const Unit& u, int wr, int wc, int fr, int fq) const {
;     ...
;             for (int m = 0; m < 4; ++m) { const int row = row0 + ai * HALF + m * 16; bf16_t* rowp = O + (size_t)row * ldc + col0; float s = 0.f, q = 0.f;
;                 const float rstd = rsv[ai][m];
; #pragma unroll
;                 for (int bj = 0; bj < 2; ++bj) { f32x4 v0 = acc[ai][bj][m][0] * rstd + bv[bj][0], v1 = acc[ai][bj][m][1] * rstd + bv[bj][1];
;                     if (ACT == 1) {
; #pragma unroll
;                         for (int e = 0; e < 4; ++e) { const float a = fmaxf(v0[e], 0.f), b2 = fmaxf(v1[e], 0.f); v0[e] = a * a; v1[e] = b2 * b2; } }
;                     if (ACT == 2) {
; #pragma unroll
;                         for (int e = 0; e < 4; ++e) { v0[e] = gelu_tanh(v0[e]); v1[e] = gelu_tanh(v1[e]); s += v0[e] + v1[e]; q += v0[e] * v0[e] + v1[e] * v1[e]; } }
;                     u32x4 w; w.x = cvt_pk_bf16(v0[0], v0[1]); w.y = cvt_pk_bf16(v0[2], v0[3]); w.z = cvt_pk_bf16(v1[0], v1[1]); w.w = cvt_pk_bf16(v1[2], v1[3]);
;                     *(u32x4*)(rowp + bj * HALF) = w; }
;                 if (ACT == 2) { if (u.pn >= 8) { s += __shfl_xor(s, 16); s += __shfl_xor(s, 32); q += __shfl_xor(q, 16); q += __shfl_xor(q, 32);
;                     if (fq == 0) *(f32x2*)(stats + ((size_t)row * 32 + (u.pn - 8) * 4 + wc) * 2) = (f32x2){s, q}; } }
	v_rcp_f32_e32 v192, v192
	v_rcp_f32_e32 v193, v193
	v_rcp_f32_e32 v194, v194
	v_rcp_f32_e32 v195, v195
	s_nop 0
	v_pk_fma_f32 v[84:85], v[84:85], v[188:189], v[84:85] neg_lo:[1,0,0] neg_hi:[1,0,0]
	v_pk_fma_f32 v[86:87], v[86:87], v[190:191], v[86:87] neg_lo:[1,0,0] neg_hi:[1,0,0]
	v_pk_fma_f32 v[80:81], v[80:81], v[192:193], v[80:81] neg_lo:[1,0,0] neg_hi:[1,0,0]
	v_pk_fma_f32 v[82:83], v[82:83], v[194:195], v[82:83] neg_lo:[1,0,0] neg_hi:[1,0,0]
	v_pk_fma_f32 v[220:221], v[84:85], v[84:85], v[220:221]
	v_pk_add_f32 v[198:199], v[198:199], v[84:85]
	v_pk_fma_f32 v[220:221], v[86:87], v[86:87], v[220:221]
	v_pk_add_f32 v[198:199], v[198:199], v[86:87]
	v_pk_fma_f32 v[220:221], v[80:81], v[80:81], v[220:221]
	v_pk_add_f32 v[198:199], v[198:199], v[80:81]
	v_pk_fma_f32 v[220:221], v[82:83], v[82:83], v[220:221]
	v_pk_add_f32 v[198:199], v[198:199], v[82:83]
	v_cvt_pk_bf16_f32 v164, v84, v85
	v_cvt_pk_bf16_f32 v165, v86, v87
	v_cvt_pk_bf16_f32 v166, v80, v81
	v_cvt_pk_bf16_f32 v167, v82, v83
	global_store_dwordx4 v[208:209], v[164:167], off offset:256 sc1
	v_add_f32_e32 v210, v198, v199
	v_add_f32_e32 v211, v220, v221
	v_mov_b32_e32 v198, v210
	v_mov_b32_e32 v199, v210
	v_mov_b32_e32 v220, v211
	v_mov_b32_e32 v221, v211
	s_nop 1
	v_permlane16_swap_b32_e32 v198, v199
	v_permlane16_swap_b32_e32 v220, v221
	v_add_f32_e32 v210, v198, v199
	v_add_f32_e32 v211, v220, v221
	v_mov_b32_e32 v198, v210
	v_mov_b32_e32 v199, v210
	v_mov_b32_e32 v220, v211
	v_mov_b32_e32 v221, v211
	s_nop 1
	v_permlane32_swap_b32_e32 v198, v199
	v_permlane32_swap_b32_e32 v220, v221
	v_add_f32_e32 v210, v198, v199
	v_add_f32_e32 v211, v220, v221
	s_and_saveexec_b64 s[16:17], s[38:39]
	global_store_dwordx2 v[222:223], v[210:211], off
	s_or_b64 exec, exec, s[16:17]
	s_mov_b64 s[16:17], 0x5000
	v_lshl_add_u64 v[222:223], v[222:223], 0, s[16:17]
	v_pk_fma_f32 v[76:77], v[76:77], v[152:153], v[32:33] op_sel_hi:[1,0,1]
	v_pk_fma_f32 v[78:79], v[78:79], v[152:153], v[34:35] op_sel_hi:[1,0,1]
	v_pk_fma_f32 v[72:73], v[72:73], v[152:153], v[36:37] op_sel_hi:[1,0,1]
	v_pk_fma_f32 v[74:75], v[74:75], v[152:153], v[38:39] op_sel_hi:[1,0,1]
	s_mov_b64 s[16:17], 0xa0000
	v_lshl_add_u64 v[208:209], v[208:209], 0, s[16:17]
	v_pk_mul_f32 v[180:181], v[76:77], v[76:77]
	v_pk_mul_f32 v[182:183], v[78:79], v[78:79]
	v_pk_mul_f32 v[184:185], v[72:73], v[72:73]
	v_pk_mul_f32 v[186:187], v[74:75], v[74:75]
	v_pk_fma_f32 v[180:181], v[180:181], v[200:201], v[206:207] op_sel_hi:[1,0,0]
	v_pk_fma_f32 v[182:183], v[182:183], v[200:201], v[206:207] op_sel_hi:[1,0,0]
	v_pk_fma_f32 v[184:185], v[184:185], v[200:201], v[206:207] op_sel_hi:[1,0,0]
	v_pk_fma_f32 v[186:187], v[186:187], v[200:201], v[206:207] op_sel_hi:[1,0,0]
	v_pk_mul_f32 v[180:181], v[180:181], v[76:77]
	v_pk_mul_f32 v[182:183], v[182:183], v[78:79]
	v_pk_mul_f32 v[184:185], v[184:185], v[72:73]
	v_pk_mul_f32 v[186:187], v[186:187], v[74:75]
	v_exp_f32_e32 v188, v180
	v_exp_f32_e32 v189, v181
	v_exp_f32_e32 v190, v182
	v_exp_f32_e32 v191, v183
	v_exp_f32_e32 v192, v184
	v_exp_f32_e32 v193, v185
	v_exp_f32_e32 v194, v186
	v_exp_f32_e32 v195, v187
	v_pk_add_f32 v[188:189], v[188:189], v[196:197] op_sel_hi:[1,0]
	v_pk_add_f32 v[190:191], v[190:191], v[196:197] op_sel_hi:[1,0]
	v_pk_add_f32 v[192:193], v[192:193], v[196:197] op_sel_hi:[1,0]
	v_pk_add_f32 v[194:195], v[194:195], v[196:197] op_sel_hi:[1,0]
	v_rcp_f32_e32 v188, v188
	v_rcp_f32_e32 v189, v189
	v_rcp_f32_e32 v190, v190
	v_rcp_f32_e32 v191, v191
	v_rcp_f32_e32 v192, v192
	v_rcp_f32_e32 v193, v193
	v_rcp_f32_e32 v194, v194
	v_rcp_f32_e32 v195, v195
	s_nop 0
	v_pk_fma_f32 v[76:77], v[76:77], v[188:189], v[76:77] neg_lo:[1,0,0] neg_hi:[1,0,0]
	v_pk_fma_f32 v[78:79], v[78:79], v[190:191], v[78:79] neg_lo:[1,0,0] neg_hi:[1,0,0]
	v_pk_fma_f32 v[72:73], v[72:73], v[192:193], v[72:73] neg_lo:[1,0,0] neg_hi:[1,0,0]
	v_pk_fma_f32 v[74:75], v[74:75], v[194:195], v[74:75] neg_lo:[1,0,0] neg_hi:[1,0,0]
	v_pk_mul_f32 v[220:221], v[76:77], v[76:77]
	v_pk_add_f32 v[198:199], v[76:77], v[78:79]
	v_pk_fma_f32 v[220:221], v[78:79], v[78:79], v[220:221]
	v_pk_fma_f32 v[220:221], v[72:73], v[72:73], v[220:221]
	v_pk_add_f32 v[198:199], v[198:199], v[72:73]
	v_pk_fma_f32 v[220:221], v[74:75], v[74:75], v[220:221]
	v_pk_add_f32 v[198:199], v[198:199], v[74:75]
	v_cvt_pk_bf16_f32 v160, v76, v77
	v_cvt_pk_bf16_f32 v161, v78, v79
	v_cvt_pk_bf16_f32 v162, v72, v73
	v_cvt_pk_bf16_f32 v163, v74, v75
	global_store_dwordx4 v[208:209], v[160:163], off sc1
	v_pk_fma_f32 v[68:69], v[68:69], v[152:153], v[40:41] op_sel_hi:[1,0,1]
	v_pk_fma_f32 v[70:71], v[70:71], v[152:153], v[42:43] op_sel_hi:[1,0,1]
	v_pk_fma_f32 v[64:65], v[64:65], v[152:153], v[44:45] op_sel_hi:[1,0,1]
	v_pk_fma_f32 v[66:67], v[66:67], v[152:153], v[46:47] op_sel_hi:[1,0,1]
	v_pk_mul_f32 v[180:181], v[68:69], v[68:69]
	v_pk_mul_f32 v[182:183], v[70:71], v[70:71]
	v_pk_mul_f32 v[184:185], v[64:65], v[64:65]
	v_pk_mul_f32 v[186:187], v[66:67], v[66:67]
	v_pk_fma_f32 v[180:181], v[180:181], v[200:201], v[206:207] op_sel_hi:[1,0,0]
	v_pk_fma_f32 v[182:183], v[182:183], v[200:201], v[206:207] op_sel_hi:[1,0,0]
	v_pk_fma_f32 v[184:185], v[184:185], v[200:201], v[206:207] op_sel_hi:[1,0,0]
	v_pk_fma_f32 v[186:187], v[186:187], v[200:201], v[206:207] op_sel_hi:[1,0,0]
	v_pk_mul_f32 v[180:181], v[180:181], v[68:69]
	v_pk_mul_f32 v[182:183], v[182:183], v[70:71]
	v_pk_mul_f32 v[184:185], v[184:185], v[64:65]
	v_pk_mul_f32 v[186:187], v[186:187], v[66:67]
	v_exp_f32_e32 v188, v180
	v_exp_f32_e32 v189, v181
	v_exp_f32_e32 v190, v182
	v_exp_f32_e32 v191, v183
	v_exp_f32_e32 v192, v184
	v_exp_f32_e32 v193, v185
	v_exp_f32_e32 v194, v186
	v_exp_f32_e32 v195, v187
; __device__ __forceinline__ unsigned cvt_pk_bf16(float lo, float hi) { unsigned r; asm volatile("v_cvt_pk_bf16_f32 %0, %1, %2" : "=v"(r) : "v"(lo), "v"(hi)); return r; }
; __device__ __forceinline__ float gelu_tanh(float x) {
;     const float u = x * (0.7978845608f + 0.0356774081f * x * x);
;     const float e = __builtin_amdgcn_exp2f(u * 2.8853900818f);
;     return x - x * __builtin_amdgcn_rcpf(e + 1.0f);
; }
;     __device__ __forceinline__ void operator()(const f32x4 (&acc)[2][2][4][2], const Unit& u, int wr, int wc, int fr, int fq) const {
;     ...
;             for (int m = 0; m < 4; ++m) { const int row = row0 + ai * HALF + m * 16; bf16_t* rowp = O + (size_t)row * ldc + col0; float s = 0.f, q = 0.f;
;                 const float rstd = rsv[ai][m];
; #pragma unroll
;                 for (int bj = 0; bj < 2; ++bj) { f32x4 v0 = acc[ai][bj][m][0] * rstd + bv[bj][0], v1 = acc[ai][bj][m][1] * rstd + bv[bj][1];
;                     if (ACT == 1) {
; #pragma unroll
;                         for (int e = 0; e < 4; ++e) { const float a = fmaxf(v0[e], 0.f), b2 = fmaxf(v1[e], 0.f); v0[e] = a * a; v1[e] = b2 * b2; } }
;                     if (ACT == 2) {
; #pragma unroll
;                         for (int e = 0; e < 4; ++e) { v0[e] = gelu_tanh(v0[e]); v1[e] = gelu_tanh(v1[e]); s += v0[e] + v1[e]; q += v0[e] * v0[e] + v1[e] * v1[e]; } }
;                     u32x4 w; w.x = cvt_pk_bf16(v0[0], v0[1]); w.y = cvt_pk_bf16(v0[2], v0[3]); w.z = cvt_pk_bf16(v1[0], v1[1]); w.w = cvt_pk_bf16(v1[2], v1[3]);
;                     *(u32x4*)(rowp + bj * HALF) = w; }
;                 if (ACT == 2) { if (u.pn >= 8) { s += __shfl_xor(s, 16); s += __shfl_xor(s, 32); q += __shfl_xor(q, 16); q += __shfl_xor(q, 32);
;                     if (fq == 0) *(f32x2*)(stats + ((size_t)row * 32 + (u.pn - 8) * 4 + wc) * 2) = (f32x2){s, q}; } }
	v_pk_add_f32 v[188:189], v[188:189], v[196:197] op_sel_hi:[1,0]
	v_pk_add_f32 v[190:191], v[190:191], v[196:197] op_sel_hi:[1,0]
	v_pk_add_f32 v[192:193], v[192:193], v[196:197] op_sel_hi:[1,0]
	v_pk_add_f32 v[194:195], v[194:195], v[196:197] op_sel_hi:[1,0]
	v_rcp_f32_e32 v188, v188
	v_rcp_f32_e32 v189, v189
	v_rcp_f32_e32 v190, v190
	v_rcp_f32_e32 v191, v191
	v_rcp_f32_e32 v192, v192
	v_rcp_f32_e32 v193, v193
	v_rcp_f32_e32 v194, v194
	v_rcp_f32_e32 v195, v195
	s_nop 0
	v_pk_fma_f32 v[68:69], v[68:69], v[188:189], v[68:69] neg_lo:[1,0,0] neg_hi:[1,0,0]
	v_pk_fma_f32 v[70:71], v[70:71], v[190:191], v[70:71] neg_lo:[1,0,0] neg_hi:[1,0,0]
	v_pk_fma_f32 v[64:65], v[64:65], v[192:193], v[64:65] neg_lo:[1,0,0] neg_hi:[1,0,0]
	v_pk_fma_f32 v[66:67], v[66:67], v[194:195], v[66:67] neg_lo:[1,0,0] neg_hi:[1,0,0]
	v_pk_fma_f32 v[220:221], v[68:69], v[68:69], v[220:221]
	v_pk_add_f32 v[198:199], v[198:199], v[68:69]
	v_pk_fma_f32 v[220:221], v[70:71], v[70:71], v[220:221]
	v_pk_add_f32 v[198:199], v[198:199], v[70:71]
	v_pk_fma_f32 v[220:221], v[64:65], v[64:65], v[220:221]
	v_pk_add_f32 v[198:199], v[198:199], v[64:65]
	v_pk_fma_f32 v[220:221], v[66:67], v[66:67], v[220:221]
	v_pk_add_f32 v[198:199], v[198:199], v[66:67]
	v_cvt_pk_bf16_f32 v164, v68, v69
	v_cvt_pk_bf16_f32 v165, v70, v71
	v_cvt_pk_bf16_f32 v166, v64, v65
	v_cvt_pk_bf16_f32 v167, v66, v67
	global_store_dwordx4 v[208:209], v[164:167], off offset:256 sc1
	v_add_f32_e32 v210, v198, v199
	v_add_f32_e32 v211, v220, v221
	v_mov_b32_e32 v198, v210
	v_mov_b32_e32 v199, v210
	v_mov_b32_e32 v220, v211
	v_mov_b32_e32 v221, v211
	s_nop 1
	v_permlane16_swap_b32_e32 v198, v199
	v_permlane16_swap_b32_e32 v220, v221
	v_add_f32_e32 v210, v198, v199
	v_add_f32_e32 v211, v220, v221
	v_mov_b32_e32 v198, v210
	v_mov_b32_e32 v199, v210
	v_mov_b32_e32 v220, v211
	v_mov_b32_e32 v221, v211
	s_nop 1
	v_permlane32_swap_b32_e32 v198, v199
	v_permlane32_swap_b32_e32 v220, v221
	v_add_f32_e32 v210, v198, v199
	v_add_f32_e32 v211, v220, v221
	s_and_saveexec_b64 s[16:17], s[38:39]
	global_store_dwordx2 v[222:223], v[210:211], off
	s_or_b64 exec, exec, s[16:17]
	s_mov_b64 s[16:17], 0x1000
	v_lshl_add_u64 v[222:223], v[222:223], 0, s[16:17]
	v_pk_fma_f32 v[60:61], v[60:61], v[154:155], v[32:33] op_sel_hi:[1,0,1]
	v_pk_fma_f32 v[62:63], v[62:63], v[154:155], v[34:35] op_sel_hi:[1,0,1]
	v_pk_fma_f32 v[56:57], v[56:57], v[154:155], v[36:37] op_sel_hi:[1,0,1]
	v_pk_fma_f32 v[58:59], v[58:59], v[154:155], v[38:39] op_sel_hi:[1,0,1]
	v_lshl_add_u64 v[208:209], v[208:209], 0, s[42:43]
	v_pk_mul_f32 v[180:181], v[60:61], v[60:61]
	v_pk_mul_f32 v[182:183], v[62:63], v[62:63]
	v_pk_mul_f32 v[184:185], v[56:57], v[56:57]
	v_pk_mul_f32 v[186:187], v[58:59], v[58:59]
	v_pk_fma_f32 v[180:181], v[180:181], v[200:201], v[206:207] op_sel_hi:[1,0,0]
	v_pk_fma_f32 v[182:183], v[182:183], v[200:201], v[206:207] op_sel_hi:[1,0,0]
	v_pk_fma_f32 v[184:185], v[184:185], v[200:201], v[206:207] op_sel_hi:[1,0,0]
	v_pk_fma_f32 v[186:187], v[186:187], v[200:201], v[206:207] op_sel_hi:[1,0,0]
	v_pk_mul_f32 v[180:181], v[180:181], v[60:61]
	v_pk_mul_f32 v[182:183], v[182:183], v[62:63]
	v_pk_mul_f32 v[184:185], v[184:185], v[56:57]
	v_pk_mul_f32 v[186:187], v[186:187], v[58:59]
	v_exp_f32_e32 v188, v180
	v_exp_f32_e32 v189, v181
	v_exp_f32_e32 v190, v182
	v_exp_f32_e32 v191, v183
	v_exp_f32_e32 v192, v184
	v_exp_f32_e32 v193, v185
	v_exp_f32_e32 v194, v186
	v_exp_f32_e32 v195, v187
	v_pk_add_f32 v[188:189], v[188:189], v[196:197] op_sel_hi:[1,0]
	v_pk_add_f32 v[190:191], v[190:191], v[196:197] op_sel_hi:[1,0]
	v_pk_add_f32 v[192:193], v[192:193], v[196:197] op_sel_hi:[1,0]
	v_pk_add_f32 v[194:195], v[194:195], v[196:197] op_sel_hi:[1,0]
	v_rcp_f32_e32 v188, v188
	v_rcp_f32_e32 v189, v189
	v_rcp_f32_e32 v190, v190
	v_rcp_f32_e32 v191, v191
	v_rcp_f32_e32 v192, v192
	v_rcp_f32_e32 v193, v193
	v_rcp_f32_e32 v194, v194
	v_rcp_f32_e32 v195, v195
	s_nop 0
	v_pk_fma_f32 v[60:61], v[60:61], v[188:189], v[60:61] neg_lo:[1,0,0] neg_hi:[1,0,0]
	v_pk_fma_f32 v[62:63], v[62:63], v[190:191], v[62:63] neg_lo:[1,0,0] neg_hi:[1,0,0]
	v_pk_fma_f32 v[56:57], v[56:57], v[192:193], v[56:57] neg_lo:[1,0,0] neg_hi:[1,0,0]
	v_pk_fma_f32 v[58:59], v[58:59], v[194:195], v[58:59] neg_lo:[1,0,0] neg_hi:[1,0,0]
	v_pk_mul_f32 v[220:221], v[60:61], v[60:61]
	v_pk_add_f32 v[198:199], v[60:61], v[62:63]
	v_pk_fma_f32 v[220:221], v[62:63], v[62:63], v[220:221]
	v_pk_fma_f32 v[220:221], v[56:57], v[56:57], v[220:221]
	v_pk_add_f32 v[198:199], v[198:199], v[56:57]
	v_pk_fma_f32 v[220:221], v[58:59], v[58:59], v[220:221]
	v_pk_add_f32 v[198:199], v[198:199], v[58:59]
	v_cvt_pk_bf16_f32 v160, v60, v61
	v_cvt_pk_bf16_f32 v161, v62, v63
	v_cvt_pk_bf16_f32 v162, v56, v57
	v_cvt_pk_bf16_f32 v163, v58, v59
	global_store_dwordx4 v[208:209], v[160:163], off sc1
	v_pk_fma_f32 v[52:53], v[52:53], v[154:155], v[40:41] op_sel_hi:[1,0,1]
	v_pk_fma_f32 v[54:55], v[54:55], v[154:155], v[42:43] op_sel_hi:[1,0,1]
	v_pk_fma_f32 v[48:49], v[48:49], v[154:155], v[44:45] op_sel_hi:[1,0,1]
	v_pk_fma_f32 v[50:51], v[50:51], v[154:155], v[46:47] op_sel_hi:[1,0,1]
	v_pk_mul_f32 v[180:181], v[52:53], v[52:53]
	v_pk_mul_f32 v[182:183], v[54:55], v[54:55]
	v_pk_mul_f32 v[184:185], v[48:49], v[48:49]
	v_pk_mul_f32 v[186:187], v[50:51], v[50:51]
	v_pk_fma_f32 v[180:181], v[180:181], v[200:201], v[206:207] op_sel_hi:[1,0,0]
	v_pk_fma_f32 v[182:183], v[182:183], v[200:201], v[206:207] op_sel_hi:[1,0,0]
	v_pk_fma_f32 v[184:185], v[184:185], v[200:201], v[206:207] op_sel_hi:[1,0,0]
	v_pk_fma_f32 v[186:187], v[186:187], v[200:201], v[206:207] op_sel_hi:[1,0,0]
	v_pk_mul_f32 v[180:181], v[180:181], v[52:53]
; __device__ __forceinline__ unsigned cvt_pk_bf16(float lo, float hi) { unsigned r; asm volatile("v_cvt_pk_bf16_f32 %0, %1, %2" : "=v"(r) : "v"(lo), "v"(hi)); return r; }
; __device__ __forceinline__ float gelu_tanh(float x) {
;     const float u = x * (0.7978845608f + 0.0356774081f * x * x);
;     const float e = __builtin_amdgcn_exp2f(u * 2.8853900818f);
;     return x - x * __builtin_amdgcn_rcpf(e + 1.0f);
; }
;     __device__ __forceinline__ void operator()(const f32x4 (&acc)[2][2][4][2], const Unit& u, int wr, int wc, int fr, int fq) const {
;     ...
;             for (int m = 0; m < 4; ++m) { const int row = row0 + ai * HALF + m * 16; bf16_t* rowp = O + (size_t)row * ldc + col0; float s = 0.f, q = 0.f;
;                 const float rstd = rsv[ai][m];
; #pragma unroll
;                 for (int bj = 0; bj < 2; ++bj) { f32x4 v0 = acc[ai][bj][m][0] * rstd + bv[bj][0], v1 = acc[ai][bj][m][1] * rstd + bv[bj][1];
;                     if (ACT == 1) {
; #pragma unroll
;                         for (int e = 0; e < 4; ++e) { const float a = fmaxf(v0[e], 0.f), b2 = fmaxf(v1[e], 0.f); v0[e] = a * a; v1[e] = b2 * b2; } }
;                     if (ACT == 2) {
; #pragma unroll
;                         for (int e = 0; e < 4; ++e) { v0[e] = gelu_tanh(v0[e]); v1[e] = gelu_tanh(v1[e]); s += v0[e] + v1[e]; q += v0[e] * v0[e] + v1[e] * v1[e]; } }
;                     u32x4 w; w.x = cvt_pk_bf16(v0[0], v0[1]); w.y = cvt_pk_bf16(v0[2], v0[3]); w.z = cvt_pk_bf16(v1[0], v1[1]); w.w = cvt_pk_bf16(v1[2], v1[3]);
;                     *(u32x4*)(rowp + bj * HALF) = w; }
;                 if (ACT == 2) { if (u.pn >= 8) { s += __shfl_xor(s, 16); s += __shfl_xor(s, 32); q += __shfl_xor(q, 16); q += __shfl_xor(q, 32);
;                     if (fq == 0) *(f32x2*)(stats + ((size_t)row * 32 + (u.pn - 8) * 4 + wc) * 2) = (f32x2){s, q}; } }
	v_pk_mul_f32 v[182:183], v[182:183], v[54:55]
	v_pk_mul_f32 v[184:185], v[184:185], v[48:49]
	v_pk_mul_f32 v[186:187], v[186:187], v[50:51]
	v_exp_f32_e32 v188, v180
	v_exp_f32_e32 v189, v181
	v_exp_f32_e32 v190, v182
	v_exp_f32_e32 v191, v183
	v_exp_f32_e32 v192, v184
	v_exp_f32_e32 v193, v185
	v_exp_f32_e32 v194, v186
	v_exp_f32_e32 v195, v187
	v_pk_add_f32 v[188:189], v[188:189], v[196:197] op_sel_hi:[1,0]
	v_pk_add_f32 v[190:191], v[190:191], v[196:197] op_sel_hi:[1,0]
	v_pk_add_f32 v[192:193], v[192:193], v[196:197] op_sel_hi:[1,0]
	v_pk_add_f32 v[194:195], v[194:195], v[196:197] op_sel_hi:[1,0]
	v_rcp_f32_e32 v188, v188
	v_rcp_f32_e32 v189, v189
	v_rcp_f32_e32 v190, v190
	v_rcp_f32_e32 v191, v191
	v_rcp_f32_e32 v192, v192
	v_rcp_f32_e32 v193, v193
	v_rcp_f32_e32 v194, v194
	v_rcp_f32_e32 v195, v195
	s_nop 0
	v_pk_fma_f32 v[52:53], v[52:53], v[188:189], v[52:53] neg_lo:[1,0,0] neg_hi:[1,0,0]
	v_pk_fma_f32 v[54:55], v[54:55], v[190:191], v[54:55] neg_lo:[1,0,0] neg_hi:[1,0,0]
	v_pk_fma_f32 v[48:49], v[48:49], v[192:193], v[48:49] neg_lo:[1,0,0] neg_hi:[1,0,0]
	v_pk_fma_f32 v[50:51], v[50:51], v[194:195], v[50:51] neg_lo:[1,0,0] neg_hi:[1,0,0]
	v_pk_fma_f32 v[220:221], v[52:53], v[52:53], v[220:221]
	v_pk_add_f32 v[198:199], v[198:199], v[52:53]
	v_pk_fma_f32 v[220:221], v[54:55], v[54:55], v[220:221]
	v_pk_add_f32 v[198:199], v[198:199], v[54:55]
	v_pk_fma_f32 v[220:221], v[48:49], v[48:49], v[220:221]
	v_pk_add_f32 v[198:199], v[198:199], v[48:49]
	v_pk_fma_f32 v[220:221], v[50:51], v[50:51], v[220:221]
	v_pk_add_f32 v[198:199], v[198:199], v[50:51]
	v_cvt_pk_bf16_f32 v164, v52, v53
	v_cvt_pk_bf16_f32 v165, v54, v55
	v_cvt_pk_bf16_f32 v166, v48, v49
	v_cvt_pk_bf16_f32 v167, v50, v51
	global_store_dwordx4 v[208:209], v[164:167], off offset:256 sc1
	v_add_f32_e32 v210, v198, v199
	v_add_f32_e32 v211, v220, v221
	v_mov_b32_e32 v198, v210
	v_mov_b32_e32 v199, v210
	v_mov_b32_e32 v220, v211
	v_mov_b32_e32 v221, v211
	s_nop 1
	v_permlane16_swap_b32_e32 v198, v199
	v_permlane16_swap_b32_e32 v220, v221
	v_add_f32_e32 v210, v198, v199
	v_add_f32_e32 v211, v220, v221
	v_mov_b32_e32 v198, v210
	v_mov_b32_e32 v199, v210
	v_mov_b32_e32 v220, v211
	v_mov_b32_e32 v221, v211
	s_nop 1
	v_permlane32_swap_b32_e32 v198, v199
	v_permlane32_swap_b32_e32 v220, v221
	v_add_f32_e32 v210, v198, v199
	v_add_f32_e32 v211, v220, v221
	s_and_saveexec_b64 s[16:17], s[38:39]
	global_store_dwordx2 v[222:223], v[210:211], off
	s_or_b64 exec, exec, s[16:17]
	s_mov_b64 s[16:17], 0x1000
	v_lshl_add_u64 v[222:223], v[222:223], 0, s[16:17]
	v_pk_fma_f32 v[28:29], v[28:29], v[156:157], v[32:33] op_sel_hi:[1,0,1]
	v_pk_fma_f32 v[30:31], v[30:31], v[156:157], v[34:35] op_sel_hi:[1,0,1]
	v_pk_fma_f32 v[24:25], v[24:25], v[156:157], v[36:37] op_sel_hi:[1,0,1]
	v_pk_fma_f32 v[26:27], v[26:27], v[156:157], v[38:39] op_sel_hi:[1,0,1]
	v_lshl_add_u64 v[208:209], v[208:209], 0, s[42:43]
	v_pk_mul_f32 v[180:181], v[28:29], v[28:29]
	v_pk_mul_f32 v[182:183], v[30:31], v[30:31]
	v_pk_mul_f32 v[184:185], v[24:25], v[24:25]
	v_pk_mul_f32 v[186:187], v[26:27], v[26:27]
	v_pk_fma_f32 v[180:181], v[180:181], v[200:201], v[206:207] op_sel_hi:[1,0,0]
	v_pk_fma_f32 v[182:183], v[182:183], v[200:201], v[206:207] op_sel_hi:[1,0,0]
	v_pk_fma_f32 v[184:185], v[184:185], v[200:201], v[206:207] op_sel_hi:[1,0,0]
	v_pk_fma_f32 v[186:187], v[186:187], v[200:201], v[206:207] op_sel_hi:[1,0,0]
	v_pk_mul_f32 v[180:181], v[180:181], v[28:29]
	v_pk_mul_f32 v[182:183], v[182:183], v[30:31]
	v_pk_mul_f32 v[184:185], v[184:185], v[24:25]
	v_pk_mul_f32 v[186:187], v[186:187], v[26:27]
	v_exp_f32_e32 v188, v180
	v_exp_f32_e32 v189, v181
	v_exp_f32_e32 v190, v182
	v_exp_f32_e32 v191, v183
	v_exp_f32_e32 v192, v184
	v_exp_f32_e32 v193, v185
	v_exp_f32_e32 v194, v186
	v_exp_f32_e32 v195, v187
	v_pk_add_f32 v[188:189], v[188:189], v[196:197] op_sel_hi:[1,0]
	v_pk_add_f32 v[190:191], v[190:191], v[196:197] op_sel_hi:[1,0]
	v_pk_add_f32 v[192:193], v[192:193], v[196:197] op_sel_hi:[1,0]
	v_pk_add_f32 v[194:195], v[194:195], v[196:197] op_sel_hi:[1,0]
	v_rcp_f32_e32 v188, v188
	v_rcp_f32_e32 v189, v189
	v_rcp_f32_e32 v190, v190
	v_rcp_f32_e32 v191, v191
	v_rcp_f32_e32 v192, v192
	v_rcp_f32_e32 v193, v193
	v_rcp_f32_e32 v194, v194
	v_rcp_f32_e32 v195, v195
	s_nop 0
	v_pk_fma_f32 v[28:29], v[28:29], v[188:189], v[28:29] neg_lo:[1,0,0] neg_hi:[1,0,0]
	v_pk_fma_f32 v[30:31], v[30:31], v[190:191], v[30:31] neg_lo:[1,0,0] neg_hi:[1,0,0]
	v_pk_fma_f32 v[24:25], v[24:25], v[192:193], v[24:25] neg_lo:[1,0,0] neg_hi:[1,0,0]
	v_pk_fma_f32 v[26:27], v[26:27], v[194:195], v[26:27] neg_lo:[1,0,0] neg_hi:[1,0,0]
	v_pk_mul_f32 v[220:221], v[28:29], v[28:29]
	v_pk_add_f32 v[198:199], v[28:29], v[30:31]
	v_pk_fma_f32 v[220:221], v[30:31], v[30:31], v[220:221]
	v_pk_fma_f32 v[220:221], v[24:25], v[24:25], v[220:221]
	v_pk_add_f32 v[198:199], v[198:199], v[24:25]
	v_pk_fma_f32 v[220:221], v[26:27], v[26:27], v[220:221]
	v_pk_add_f32 v[198:199], v[198:199], v[26:27]
	v_cvt_pk_bf16_f32 v160, v28, v29
	v_cvt_pk_bf16_f32 v161, v30, v31
	v_cvt_pk_bf16_f32 v162, v24, v25
	v_cvt_pk_bf16_f32 v163, v26, v27
	global_store_dwordx4 v[208:209], v[160:163], off sc1
	v_pk_fma_f32 v[20:21], v[20:21], v[156:157], v[40:41] op_sel_hi:[1,0,1]
	v_pk_fma_f32 v[22:23], v[22:23], v[156:157], v[42:43] op_sel_hi:[1,0,1]
	v_pk_fma_f32 v[16:17], v[16:17], v[156:157], v[44:45] op_sel_hi:[1,0,1]
	v_pk_fma_f32 v[18:19], v[18:19], v[156:157], v[46:47] op_sel_hi:[1,0,1]
	v_pk_mul_f32 v[180:181], v[20:21], v[20:21]
	v_pk_mul_f32 v[182:183], v[22:23], v[22:23]
	v_pk_mul_f32 v[184:185], v[16:17], v[16:17]
	v_pk_mul_f32 v[186:187], v[18:19], v[18:19]
; __device__ __forceinline__ unsigned cvt_pk_bf16(float lo, float hi) { unsigned r; asm volatile("v_cvt_pk_bf16_f32 %0, %1, %2" : "=v"(r) : "v"(lo), "v"(hi)); return r; }
; __device__ __forceinline__ float gelu_tanh(float x) {
;     const float u = x * (0.7978845608f + 0.0356774081f * x * x);
;     const float e = __builtin_amdgcn_exp2f(u * 2.8853900818f);
;     return x - x * __builtin_amdgcn_rcpf(e + 1.0f);
; }
;     __device__ __forceinline__ void operator()(const f32x4 (&acc)[2][2][4][2], const Unit& u, int wr, int wc, int fr, int fq) const {
;     ...
;             for (int m = 0; m < 4; ++m) { const int row = row0 + ai * HALF + m * 16; bf16_t* rowp = O + (size_t)row * ldc + col0; float s = 0.f, q = 0.f;
;                 const float rstd = rsv[ai][m];
; #pragma unroll
;                 for (int bj = 0; bj < 2; ++bj) { f32x4 v0 = acc[ai][bj][m][0] * rstd + bv[bj][0], v1 = acc[ai][bj][m][1] * rstd + bv[bj][1];
;                     if (ACT == 1) {
; #pragma unroll
;                         for (int e = 0; e < 4; ++e) { const float a = fmaxf(v0[e], 0.f), b2 = fmaxf(v1[e], 0.f); v0[e] = a * a; v1[e] = b2 * b2; } }
;                     if (ACT == 2) {
; #pragma unroll
;                         for (int e = 0; e < 4; ++e) { v0[e] = gelu_tanh(v0[e]); v1[e] = gelu_tanh(v1[e]); s += v0[e] + v1[e]; q += v0[e] * v0[e] + v1[e] * v1[e]; } }
;                     u32x4 w; w.x = cvt_pk_bf16(v0[0], v0[1]); w.y = cvt_pk_bf16(v0[2], v0[3]); w.z = cvt_pk_bf16(v1[0], v1[1]); w.w = cvt_pk_bf16(v1[2], v1[3]);
;                     *(u32x4*)(rowp + bj * HALF) = w; }
;                 if (ACT == 2) { if (u.pn >= 8) { s += __shfl_xor(s, 16); s += __shfl_xor(s, 32); q += __shfl_xor(q, 16); q += __shfl_xor(q, 32);
;                     if (fq == 0) *(f32x2*)(stats + ((size_t)row * 32 + (u.pn - 8) * 4 + wc) * 2) = (f32x2){s, q}; } }
	v_pk_fma_f32 v[180:181], v[180:181], v[200:201], v[206:207] op_sel_hi:[1,0,0]
	v_pk_fma_f32 v[182:183], v[182:183], v[200:201], v[206:207] op_sel_hi:[1,0,0]
	v_pk_fma_f32 v[184:185], v[184:185], v[200:201], v[206:207] op_sel_hi:[1,0,0]
	v_pk_fma_f32 v[186:187], v[186:187], v[200:201], v[206:207] op_sel_hi:[1,0,0]
	v_pk_mul_f32 v[180:181], v[180:181], v[20:21]
	v_pk_mul_f32 v[182:183], v[182:183], v[22:23]
	v_pk_mul_f32 v[184:185], v[184:185], v[16:17]
	v_pk_mul_f32 v[186:187], v[186:187], v[18:19]
	v_exp_f32_e32 v188, v180
	v_exp_f32_e32 v189, v181
	v_exp_f32_e32 v190, v182
	v_exp_f32_e32 v191, v183
	v_exp_f32_e32 v192, v184
	v_exp_f32_e32 v193, v185
	v_exp_f32_e32 v194, v186
	v_exp_f32_e32 v195, v187
	v_pk_add_f32 v[188:189], v[188:189], v[196:197] op_sel_hi:[1,0]
	v_pk_add_f32 v[190:191], v[190:191], v[196:197] op_sel_hi:[1,0]
	v_pk_add_f32 v[192:193], v[192:193], v[196:197] op_sel_hi:[1,0]
	v_pk_add_f32 v[194:195], v[194:195], v[196:197] op_sel_hi:[1,0]
	v_rcp_f32_e32 v188, v188
	v_rcp_f32_e32 v189, v189
	v_rcp_f32_e32 v190, v190
	v_rcp_f32_e32 v191, v191
	v_rcp_f32_e32 v192, v192
	v_rcp_f32_e32 v193, v193
	v_rcp_f32_e32 v194, v194
	v_rcp_f32_e32 v195, v195
	s_nop 0
	v_pk_fma_f32 v[20:21], v[20:21], v[188:189], v[20:21] neg_lo:[1,0,0] neg_hi:[1,0,0]
	v_pk_fma_f32 v[22:23], v[22:23], v[190:191], v[22:23] neg_lo:[1,0,0] neg_hi:[1,0,0]
	v_pk_fma_f32 v[16:17], v[16:17], v[192:193], v[16:17] neg_lo:[1,0,0] neg_hi:[1,0,0]
	v_pk_fma_f32 v[18:19], v[18:19], v[194:195], v[18:19] neg_lo:[1,0,0] neg_hi:[1,0,0]
	v_pk_fma_f32 v[220:221], v[20:21], v[20:21], v[220:221]
	v_pk_add_f32 v[198:199], v[198:199], v[20:21]
	v_pk_fma_f32 v[220:221], v[22:23], v[22:23], v[220:221]
	v_pk_add_f32 v[198:199], v[198:199], v[22:23]
	v_pk_fma_f32 v[220:221], v[16:17], v[16:17], v[220:221]
	v_pk_add_f32 v[198:199], v[198:199], v[16:17]
	v_pk_fma_f32 v[220:221], v[18:19], v[18:19], v[220:221]
	v_pk_add_f32 v[198:199], v[198:199], v[18:19]
	v_cvt_pk_bf16_f32 v164, v20, v21
	v_cvt_pk_bf16_f32 v165, v22, v23
	v_cvt_pk_bf16_f32 v166, v16, v17
	v_cvt_pk_bf16_f32 v167, v18, v19
	global_store_dwordx4 v[208:209], v[164:167], off offset:256 sc1
	v_add_f32_e32 v210, v198, v199
	v_add_f32_e32 v211, v220, v221
	v_mov_b32_e32 v198, v210
	v_mov_b32_e32 v199, v210
	v_mov_b32_e32 v220, v211
	v_mov_b32_e32 v221, v211
	s_nop 1
	v_permlane16_swap_b32_e32 v198, v199
	v_permlane16_swap_b32_e32 v220, v221
	v_add_f32_e32 v210, v198, v199
	v_add_f32_e32 v211, v220, v221
	v_mov_b32_e32 v198, v210
	v_mov_b32_e32 v199, v210
	v_mov_b32_e32 v220, v211
	v_mov_b32_e32 v221, v211
	s_nop 1
	v_permlane32_swap_b32_e32 v198, v199
	v_permlane32_swap_b32_e32 v220, v221
	v_add_f32_e32 v210, v198, v199
	v_add_f32_e32 v211, v220, v221
	s_and_saveexec_b64 s[16:17], s[38:39]
	global_store_dwordx2 v[222:223], v[210:211], off
	s_or_b64 exec, exec, s[16:17]
	s_mov_b64 s[16:17], 0x1000
	v_lshl_add_u64 v[222:223], v[222:223], 0, s[16:17]
	v_pk_fma_f32 v[12:13], v[12:13], v[158:159], v[32:33] op_sel_hi:[1,0,1]
	v_pk_fma_f32 v[14:15], v[14:15], v[158:159], v[34:35] op_sel_hi:[1,0,1]
	v_pk_fma_f32 v[8:9], v[8:9], v[158:159], v[36:37] op_sel_hi:[1,0,1]
	v_pk_fma_f32 v[10:11], v[10:11], v[158:159], v[38:39] op_sel_hi:[1,0,1]
	v_lshl_add_u64 v[208:209], v[208:209], 0, s[42:43]
	v_pk_mul_f32 v[180:181], v[12:13], v[12:13]
	v_pk_mul_f32 v[182:183], v[14:15], v[14:15]
	v_pk_mul_f32 v[184:185], v[8:9], v[8:9]
	v_pk_mul_f32 v[186:187], v[10:11], v[10:11]
	v_pk_fma_f32 v[180:181], v[180:181], v[200:201], v[206:207] op_sel_hi:[1,0,0]
	v_pk_fma_f32 v[182:183], v[182:183], v[200:201], v[206:207] op_sel_hi:[1,0,0]
	v_pk_fma_f32 v[184:185], v[184:185], v[200:201], v[206:207] op_sel_hi:[1,0,0]
	v_pk_fma_f32 v[186:187], v[186:187], v[200:201], v[206:207] op_sel_hi:[1,0,0]
	v_pk_mul_f32 v[180:181], v[180:181], v[12:13]
	v_pk_mul_f32 v[182:183], v[182:183], v[14:15]
	v_pk_mul_f32 v[184:185], v[184:185], v[8:9]
	v_pk_mul_f32 v[186:187], v[186:187], v[10:11]
	v_exp_f32_e32 v188, v180
	v_exp_f32_e32 v189, v181
	v_exp_f32_e32 v190, v182
	v_exp_f32_e32 v191, v183
	v_exp_f32_e32 v192, v184
	v_exp_f32_e32 v193, v185
	v_exp_f32_e32 v194, v186
	v_exp_f32_e32 v195, v187
	v_pk_add_f32 v[188:189], v[188:189], v[196:197] op_sel_hi:[1,0]
	v_pk_add_f32 v[190:191], v[190:191], v[196:197] op_sel_hi:[1,0]
	v_pk_add_f32 v[192:193], v[192:193], v[196:197] op_sel_hi:[1,0]
	v_pk_add_f32 v[194:195], v[194:195], v[196:197] op_sel_hi:[1,0]
	v_rcp_f32_e32 v188, v188
	v_rcp_f32_e32 v189, v189
	v_rcp_f32_e32 v190, v190
	v_rcp_f32_e32 v191, v191
	v_rcp_f32_e32 v192, v192
	v_rcp_f32_e32 v193, v193
	v_rcp_f32_e32 v194, v194
	v_rcp_f32_e32 v195, v195
	s_nop 0
	v_pk_fma_f32 v[12:13], v[12:13], v[188:189], v[12:13] neg_lo:[1,0,0] neg_hi:[1,0,0]
	v_pk_fma_f32 v[14:15], v[14:15], v[190:191], v[14:15] neg_lo:[1,0,0] neg_hi:[1,0,0]
	v_pk_fma_f32 v[8:9], v[8:9], v[192:193], v[8:9] neg_lo:[1,0,0] neg_hi:[1,0,0]
	v_pk_fma_f32 v[10:11], v[10:11], v[194:195], v[10:11] neg_lo:[1,0,0] neg_hi:[1,0,0]
	v_pk_mul_f32 v[220:221], v[12:13], v[12:13]
	v_pk_add_f32 v[198:199], v[12:13], v[14:15]
	v_pk_fma_f32 v[220:221], v[14:15], v[14:15], v[220:221]
	v_pk_fma_f32 v[220:221], v[8:9], v[8:9], v[220:221]
	v_pk_add_f32 v[198:199], v[198:199], v[8:9]
	v_pk_fma_f32 v[220:221], v[10:11], v[10:11], v[220:221]
	v_pk_add_f32 v[198:199], v[198:199], v[10:11]
	v_cvt_pk_bf16_f32 v160, v12, v13
	v_cvt_pk_bf16_f32 v161, v14, v15
	v_cvt_pk_bf16_f32 v162, v8, v9
	v_cvt_pk_bf16_f32 v163, v10, v11
	global_store_dwordx4 v[208:209], v[160:163], off sc1
	v_pk_fma_f32 v[4:5], v[4:5], v[158:159], v[40:41] op_sel_hi:[1,0,1]
	v_pk_fma_f32 v[6:7], v[6:7], v[158:159], v[42:43] op_sel_hi:[1,0,1]
; __device__ __forceinline__ unsigned cvt_pk_bf16(float lo, float hi) { unsigned r; asm volatile("v_cvt_pk_bf16_f32 %0, %1, %2" : "=v"(r) : "v"(lo), "v"(hi)); return r; }
; __device__ __forceinline__ float gelu_tanh(float x) {
;     const float u = x * (0.7978845608f + 0.0356774081f * x * x);
;     const float e = __builtin_amdgcn_exp2f(u * 2.8853900818f);
;     return x - x * __builtin_amdgcn_rcpf(e + 1.0f);
; }
;     __device__ __forceinline__ void operator()(const f32x4 (&acc)[2][2][4][2], const Unit& u, int wr, int wc, int fr, int fq) const {
;     ...
;             for (int m = 0; m < 4; ++m) { const int row = row0 + ai * HALF + m * 16; bf16_t* rowp = O + (size_t)row * ldc + col0; float s = 0.f, q = 0.f;
;                 const float rstd = rsv[ai][m];
; #pragma unroll
;                 for (int bj = 0; bj < 2; ++bj) { f32x4 v0 = acc[ai][bj][m][0] * rstd + bv[bj][0], v1 = acc[ai][bj][m][1] * rstd + bv[bj][1];
;                     if (ACT == 1) {
; #pragma unroll
;                         for (int e = 0; e < 4; ++e) { const float a = fmaxf(v0[e], 0.f), b2 = fmaxf(v1[e], 0.f); v0[e] = a * a; v1[e] = b2 * b2; } }
;                     if (ACT == 2) {
; #pragma unroll
;                         for (int e = 0; e < 4; ++e) { v0[e] = gelu_tanh(v0[e]); v1[e] = gelu_tanh(v1[e]); s += v0[e] + v1[e]; q += v0[e] * v0[e] + v1[e] * v1[e]; } }
;                     u32x4 w; w.x = cvt_pk_bf16(v0[0], v0[1]); w.y = cvt_pk_bf16(v0[2], v0[3]); w.z = cvt_pk_bf16(v1[0], v1[1]); w.w = cvt_pk_bf16(v1[2], v1[3]);
;                     *(u32x4*)(rowp + bj * HALF) = w; }
;                 if (ACT == 2) { if (u.pn >= 8) { s += __shfl_xor(s, 16); s += __shfl_xor(s, 32); q += __shfl_xor(q, 16); q += __shfl_xor(q, 32);
;                     if (fq == 0) *(f32x2*)(stats + ((size_t)row * 32 + (u.pn - 8) * 4 + wc) * 2) = (f32x2){s, q}; } }
	v_pk_fma_f32 v[0:1], v[0:1], v[158:159], v[44:45] op_sel_hi:[1,0,1]
	v_pk_fma_f32 v[2:3], v[2:3], v[158:159], v[46:47] op_sel_hi:[1,0,1]
	v_pk_mul_f32 v[180:181], v[4:5], v[4:5]
	v_pk_mul_f32 v[182:183], v[6:7], v[6:7]
	v_pk_mul_f32 v[184:185], v[0:1], v[0:1]
	v_pk_mul_f32 v[186:187], v[2:3], v[2:3]
	v_pk_fma_f32 v[180:181], v[180:181], v[200:201], v[206:207] op_sel_hi:[1,0,0]
	v_pk_fma_f32 v[182:183], v[182:183], v[200:201], v[206:207] op_sel_hi:[1,0,0]
	v_pk_fma_f32 v[184:185], v[184:185], v[200:201], v[206:207] op_sel_hi:[1,0,0]
	v_pk_fma_f32 v[186:187], v[186:187], v[200:201], v[206:207] op_sel_hi:[1,0,0]
	v_pk_mul_f32 v[180:181], v[180:181], v[4:5]
	v_pk_mul_f32 v[182:183], v[182:183], v[6:7]
	v_pk_mul_f32 v[184:185], v[184:185], v[0:1]
	v_pk_mul_f32 v[186:187], v[186:187], v[2:3]
	v_exp_f32_e32 v188, v180
	v_exp_f32_e32 v189, v181
	v_exp_f32_e32 v190, v182
	v_exp_f32_e32 v191, v183
	v_exp_f32_e32 v192, v184
	v_exp_f32_e32 v193, v185
	v_exp_f32_e32 v194, v186
	v_exp_f32_e32 v195, v187
	v_pk_add_f32 v[188:189], v[188:189], v[196:197] op_sel_hi:[1,0]
	v_pk_add_f32 v[190:191], v[190:191], v[196:197] op_sel_hi:[1,0]
	v_pk_add_f32 v[192:193], v[192:193], v[196:197] op_sel_hi:[1,0]
	v_pk_add_f32 v[194:195], v[194:195], v[196:197] op_sel_hi:[1,0]
	v_rcp_f32_e32 v188, v188
	v_rcp_f32_e32 v189, v189
	v_rcp_f32_e32 v190, v190
	v_rcp_f32_e32 v191, v191
	v_rcp_f32_e32 v192, v192
	v_rcp_f32_e32 v193, v193
	v_rcp_f32_e32 v194, v194
	v_rcp_f32_e32 v195, v195
	s_nop 0
	v_pk_fma_f32 v[4:5], v[4:5], v[188:189], v[4:5] neg_lo:[1,0,0] neg_hi:[1,0,0]
	v_pk_fma_f32 v[6:7], v[6:7], v[190:191], v[6:7] neg_lo:[1,0,0] neg_hi:[1,0,0]
	v_pk_fma_f32 v[0:1], v[0:1], v[192:193], v[0:1] neg_lo:[1,0,0] neg_hi:[1,0,0]
	v_pk_fma_f32 v[2:3], v[2:3], v[194:195], v[2:3] neg_lo:[1,0,0] neg_hi:[1,0,0]
	v_pk_fma_f32 v[220:221], v[4:5], v[4:5], v[220:221]
	v_pk_add_f32 v[198:199], v[198:199], v[4:5]
	v_pk_fma_f32 v[220:221], v[6:7], v[6:7], v[220:221]
	v_pk_add_f32 v[198:199], v[198:199], v[6:7]
	v_pk_fma_f32 v[220:221], v[0:1], v[0:1], v[220:221]
	v_pk_add_f32 v[198:199], v[198:199], v[0:1]
	v_pk_fma_f32 v[220:221], v[2:3], v[2:3], v[220:221]
	v_pk_add_f32 v[198:199], v[198:199], v[2:3]
	v_cvt_pk_bf16_f32 v164, v4, v5
	v_cvt_pk_bf16_f32 v165, v6, v7
	v_cvt_pk_bf16_f32 v166, v0, v1
	v_cvt_pk_bf16_f32 v167, v2, v3
	global_store_dwordx4 v[208:209], v[164:167], off offset:256 sc1
	v_add_f32_e32 v210, v198, v199
	v_add_f32_e32 v211, v220, v221
	v_mov_b32_e32 v198, v210
	v_mov_b32_e32 v199, v210
	v_mov_b32_e32 v220, v211
	v_mov_b32_e32 v221, v211
	s_nop 1
	v_permlane16_swap_b32_e32 v198, v199
	v_permlane16_swap_b32_e32 v220, v221
	v_add_f32_e32 v210, v198, v199
	v_add_f32_e32 v211, v220, v221
	v_mov_b32_e32 v198, v210
	v_mov_b32_e32 v199, v210
	v_mov_b32_e32 v220, v211
	v_mov_b32_e32 v221, v211
	s_nop 1
	v_permlane32_swap_b32_e32 v198, v199
	v_permlane32_swap_b32_e32 v220, v221
	v_add_f32_e32 v210, v198, v199
	v_add_f32_e32 v211, v220, v221
	s_and_saveexec_b64 s[16:17], s[38:39]
	global_store_dwordx2 v[222:223], v[210:211], off
	s_or_b64 exec, exec, s[16:17]
	s_branch .Lwin_epi_done
.Lwin_epi_nostats:
	v_pk_fma_f32 v[140:141], v[140:141], v[144:145], v[32:33] op_sel_hi:[1,0,1]
	v_pk_fma_f32 v[142:143], v[142:143], v[144:145], v[34:35] op_sel_hi:[1,0,1]
	v_pk_fma_f32 v[136:137], v[136:137], v[144:145], v[36:37] op_sel_hi:[1,0,1]
	v_pk_fma_f32 v[138:139], v[138:139], v[144:145], v[38:39] op_sel_hi:[1,0,1]
	v_pk_mul_f32 v[180:181], v[140:141], v[140:141]
	v_pk_mul_f32 v[182:183], v[142:143], v[142:143]
	v_pk_mul_f32 v[184:185], v[136:137], v[136:137]
	v_pk_mul_f32 v[186:187], v[138:139], v[138:139]
	v_pk_fma_f32 v[180:181], v[180:181], v[200:201], v[206:207] op_sel_hi:[1,0,0]
	v_pk_fma_f32 v[182:183], v[182:183], v[200:201], v[206:207] op_sel_hi:[1,0,0]
	v_pk_fma_f32 v[184:185], v[184:185], v[200:201], v[206:207] op_sel_hi:[1,0,0]
	v_pk_fma_f32 v[186:187], v[186:187], v[200:201], v[206:207] op_sel_hi:[1,0,0]
	v_pk_mul_f32 v[180:181], v[180:181], v[140:141]
	v_pk_mul_f32 v[182:183], v[182:183], v[142:143]
	v_pk_mul_f32 v[184:185], v[184:185], v[136:137]
	v_pk_mul_f32 v[186:187], v[186:187], v[138:139]
	v_exp_f32_e32 v188, v180
	v_exp_f32_e32 v189, v181
	v_exp_f32_e32 v190, v182
	v_exp_f32_e32 v191, v183
	v_exp_f32_e32 v192, v184
	v_exp_f32_e32 v193, v185
	v_exp_f32_e32 v194, v186
	v_exp_f32_e32 v195, v187
	v_pk_add_f32 v[188:189], v[188:189], v[196:197] op_sel_hi:[1,0]
	v_pk_add_f32 v[190:191], v[190:191], v[196:197] op_sel_hi:[1,0]
	v_pk_add_f32 v[192:193], v[192:193], v[196:197] op_sel_hi:[1,0]
	v_pk_add_f32 v[194:195], v[194:195], v[196:197] op_sel_hi:[1,0]
	v_rcp_f32_e32 v188, v188
	v_rcp_f32_e32 v189, v189
	v_rcp_f32_e32 v190, v190
	v_rcp_f32_e32 v191, v191
	v_rcp_f32_e32 v192, v192
	v_rcp_f32_e32 v193, v193
	v_rcp_f32_e32 v194, v194
	v_rcp_f32_e32 v195, v195
	s_nop 0
	v_pk_fma_f32 v[140:141], v[140:141], v[188:189], v[140:141] neg_lo:[1,0,0] neg_hi:[1,0,0]
	v_pk_fma_f32 v[142:143], v[142:143], v[190:191], v[142:143] neg_lo:[1,0,0] neg_hi:[1,0,0]
	v_pk_fma_f32 v[136:137], v[136:137], v[192:193], v[136:137] neg_lo:[1,0,0] neg_hi:[1,0,0]
	v_pk_fma_f32 v[138:139], v[138:139], v[194:195], v[138:139] neg_lo:[1,0,0] neg_hi:[1,0,0]
	v_cvt_pk_bf16_f32 v160, v140, v141
	v_cvt_pk_bf16_f32 v161, v142, v143
	v_cvt_pk_bf16_f32 v162, v136, v137
	v_cvt_pk_bf16_f32 v163, v138, v139
	global_store_dwordx4 v[208:209], v[160:163], off sc1
	v_pk_fma_f32 v[132:133], v[132:133], v[144:145], v[40:41] op_sel_hi:[1,0,1]
	v_pk_fma_f32 v[134:135], v[134:135], v[144:145], v[42:43] op_sel_hi:[1,0,1]
	v_pk_fma_f32 v[128:129], v[128:129], v[144:145], v[44:45] op_sel_hi:[1,0,1]
; __device__ __forceinline__ unsigned cvt_pk_bf16(float lo, float hi) { unsigned r; asm volatile("v_cvt_pk_bf16_f32 %0, %1, %2" : "=v"(r) : "v"(lo), "v"(hi)); return r; }
; __device__ __forceinline__ float gelu_tanh(float x) {
;     const float u = x * (0.7978845608f + 0.0356774081f * x * x);
;     const float e = __builtin_amdgcn_exp2f(u * 2.8853900818f);
;     return x - x * __builtin_amdgcn_rcpf(e + 1.0f);
;     __device__ __forceinline__ void operator()(const f32x4 (&acc)[2][2][4][2], const Unit& u, int wr, int wc, int fr, int fq) const {
;     ...
;             for (int m = 0; m < 4; ++m) { const int row = row0 + ai * HALF + m * 16; bf16_t* rowp = O + (size_t)row * ldc + col0; float s = 0.f, q = 0.f;
;                 const float rstd = rsv[ai][m];
; #pragma unroll
;                 for (int bj = 0; bj < 2; ++bj) { f32x4 v0 = acc[ai][bj][m][0] * rstd + bv[bj][0], v1 = acc[ai][bj][m][1] * rstd + bv[bj][1];
;                     if (ACT == 1) {
; #pragma unroll
;                         for (int e = 0; e < 4; ++e) { const float a = fmaxf(v0[e], 0.f), b2 = fmaxf(v1[e], 0.f); v0[e] = a * a; v1[e] = b2 * b2; } }
;                     if (ACT == 2) {
; #pragma unroll
;                         for (int e = 0; e < 4; ++e) { v0[e] = gelu_tanh(v0[e]); v1[e] = gelu_tanh(v1[e]); s += v0[e] + v1[e]; q += v0[e] * v0[e] + v1[e] * v1[e]; } }
;                     u32x4 w; w.x = cvt_pk_bf16(v0[0], v0[1]); w.y = cvt_pk_bf16(v0[2], v0[3]); w.z = cvt_pk_bf16(v1[0], v1[1]); w.w = cvt_pk_bf16(v1[2], v1[3]);
;                     *(u32x4*)(rowp + bj * HALF) = w; }
	v_pk_fma_f32 v[130:131], v[130:131], v[144:145], v[46:47] op_sel_hi:[1,0,1]
	v_pk_mul_f32 v[180:181], v[132:133], v[132:133]
	v_pk_mul_f32 v[182:183], v[134:135], v[134:135]
	v_pk_mul_f32 v[184:185], v[128:129], v[128:129]
	v_pk_mul_f32 v[186:187], v[130:131], v[130:131]
	v_pk_fma_f32 v[180:181], v[180:181], v[200:201], v[206:207] op_sel_hi:[1,0,0]
	v_pk_fma_f32 v[182:183], v[182:183], v[200:201], v[206:207] op_sel_hi:[1,0,0]
	v_pk_fma_f32 v[184:185], v[184:185], v[200:201], v[206:207] op_sel_hi:[1,0,0]
	v_pk_fma_f32 v[186:187], v[186:187], v[200:201], v[206:207] op_sel_hi:[1,0,0]
	v_pk_mul_f32 v[180:181], v[180:181], v[132:133]
	v_pk_mul_f32 v[182:183], v[182:183], v[134:135]
	v_pk_mul_f32 v[184:185], v[184:185], v[128:129]
	v_pk_mul_f32 v[186:187], v[186:187], v[130:131]
	v_exp_f32_e32 v188, v180
	v_exp_f32_e32 v189, v181
	v_exp_f32_e32 v190, v182
	v_exp_f32_e32 v191, v183
	v_exp_f32_e32 v192, v184
	v_exp_f32_e32 v193, v185
	v_exp_f32_e32 v194, v186
	v_exp_f32_e32 v195, v187
	v_pk_add_f32 v[188:189], v[188:189], v[196:197] op_sel_hi:[1,0]
	v_pk_add_f32 v[190:191], v[190:191], v[196:197] op_sel_hi:[1,0]
	v_pk_add_f32 v[192:193], v[192:193], v[196:197] op_sel_hi:[1,0]
	v_pk_add_f32 v[194:195], v[194:195], v[196:197] op_sel_hi:[1,0]
	v_rcp_f32_e32 v188, v188
	v_rcp_f32_e32 v189, v189
	v_rcp_f32_e32 v190, v190
	v_rcp_f32_e32 v191, v191
	v_rcp_f32_e32 v192, v192
	v_rcp_f32_e32 v193, v193
	v_rcp_f32_e32 v194, v194
	v_rcp_f32_e32 v195, v195
	s_nop 0
	v_pk_fma_f32 v[132:133], v[132:133], v[188:189], v[132:133] neg_lo:[1,0,0] neg_hi:[1,0,0]
	v_pk_fma_f32 v[134:135], v[134:135], v[190:191], v[134:135] neg_lo:[1,0,0] neg_hi:[1,0,0]
	v_pk_fma_f32 v[128:129], v[128:129], v[192:193], v[128:129] neg_lo:[1,0,0] neg_hi:[1,0,0]
	v_pk_fma_f32 v[130:131], v[130:131], v[194:195], v[130:131] neg_lo:[1,0,0] neg_hi:[1,0,0]
	v_cvt_pk_bf16_f32 v164, v132, v133
	v_cvt_pk_bf16_f32 v165, v134, v135
	v_cvt_pk_bf16_f32 v166, v128, v129
	v_cvt_pk_bf16_f32 v167, v130, v131
	global_store_dwordx4 v[208:209], v[164:167], off offset:256 sc1
	v_pk_fma_f32 v[124:125], v[124:125], v[146:147], v[32:33] op_sel_hi:[1,0,1]
	v_pk_fma_f32 v[126:127], v[126:127], v[146:147], v[34:35] op_sel_hi:[1,0,1]
	v_pk_fma_f32 v[120:121], v[120:121], v[146:147], v[36:37] op_sel_hi:[1,0,1]
	v_pk_fma_f32 v[122:123], v[122:123], v[146:147], v[38:39] op_sel_hi:[1,0,1]
	v_lshl_add_u64 v[208:209], v[208:209], 0, s[42:43]
	v_pk_mul_f32 v[180:181], v[124:125], v[124:125]
	v_pk_mul_f32 v[182:183], v[126:127], v[126:127]
	v_pk_mul_f32 v[184:185], v[120:121], v[120:121]
	v_pk_mul_f32 v[186:187], v[122:123], v[122:123]
	v_pk_fma_f32 v[180:181], v[180:181], v[200:201], v[206:207] op_sel_hi:[1,0,0]
	v_pk_fma_f32 v[182:183], v[182:183], v[200:201], v[206:207] op_sel_hi:[1,0,0]
	v_pk_fma_f32 v[184:185], v[184:185], v[200:201], v[206:207] op_sel_hi:[1,0,0]
	v_pk_fma_f32 v[186:187], v[186:187], v[200:201], v[206:207] op_sel_hi:[1,0,0]
	v_pk_mul_f32 v[180:181], v[180:181], v[124:125]
	v_pk_mul_f32 v[182:183], v[182:183], v[126:127]
	v_pk_mul_f32 v[184:185], v[184:185], v[120:121]
	v_pk_mul_f32 v[186:187], v[186:187], v[122:123]
	v_exp_f32_e32 v188, v180
	v_exp_f32_e32 v189, v181
	v_exp_f32_e32 v190, v182
	v_exp_f32_e32 v191, v183
	v_exp_f32_e32 v192, v184
	v_exp_f32_e32 v193, v185
	v_exp_f32_e32 v194, v186
	v_exp_f32_e32 v195, v187
	v_pk_add_f32 v[188:189], v[188:189], v[196:197] op_sel_hi:[1,0]
	v_pk_add_f32 v[190:191], v[190:191], v[196:197] op_sel_hi:[1,0]
	v_pk_add_f32 v[192:193], v[192:193], v[196:197] op_sel_hi:[1,0]
	v_pk_add_f32 v[194:195], v[194:195], v[196:197] op_sel_hi:[1,0]
	v_rcp_f32_e32 v188, v188
	v_rcp_f32_e32 v189, v189
	v_rcp_f32_e32 v190, v190
	v_rcp_f32_e32 v191, v191
	v_rcp_f32_e32 v192, v192
	v_rcp_f32_e32 v193, v193
	v_rcp_f32_e32 v194, v194
	v_rcp_f32_e32 v195, v195
	s_nop 0
	v_pk_fma_f32 v[124:125], v[124:125], v[188:189], v[124:125] neg_lo:[1,0,0] neg_hi:[1,0,0]
	v_pk_fma_f32 v[126:127], v[126:127], v[190:191], v[126:127] neg_lo:[1,0,0] neg_hi:[1,0,0]
	v_pk_fma_f32 v[120:121], v[120:121], v[192:193], v[120:121] neg_lo:[1,0,0] neg_hi:[1,0,0]
	v_pk_fma_f32 v[122:123], v[122:123], v[194:195], v[122:123] neg_lo:[1,0,0] neg_hi:[1,0,0]
	v_cvt_pk_bf16_f32 v160, v124, v125
	v_cvt_pk_bf16_f32 v161, v126, v127
	v_cvt_pk_bf16_f32 v162, v120, v121
	v_cvt_pk_bf16_f32 v163, v122, v123
	global_store_dwordx4 v[208:209], v[160:163], off sc1
	v_pk_fma_f32 v[116:117], v[116:117], v[146:147], v[40:41] op_sel_hi:[1,0,1]
	v_pk_fma_f32 v[118:119], v[118:119], v[146:147], v[42:43] op_sel_hi:[1,0,1]
	v_pk_fma_f32 v[112:113], v[112:113], v[146:147], v[44:45] op_sel_hi:[1,0,1]
	v_pk_fma_f32 v[114:115], v[114:115], v[146:147], v[46:47] op_sel_hi:[1,0,1]
	v_pk_mul_f32 v[180:181], v[116:117], v[116:117]
	v_pk_mul_f32 v[182:183], v[118:119], v[118:119]
	v_pk_mul_f32 v[184:185], v[112:113], v[112:113]
	v_pk_mul_f32 v[186:187], v[114:115], v[114:115]
	v_pk_fma_f32 v[180:181], v[180:181], v[200:201], v[206:207] op_sel_hi:[1,0,0]
	v_pk_fma_f32 v[182:183], v[182:183], v[200:201], v[206:207] op_sel_hi:[1,0,0]
	v_pk_fma_f32 v[184:185], v[184:185], v[200:201], v[206:207] op_sel_hi:[1,0,0]
	v_pk_fma_f32 v[186:187], v[186:187], v[200:201], v[206:207] op_sel_hi:[1,0,0]
	v_pk_mul_f32 v[180:181], v[180:181], v[116:117]
	v_pk_mul_f32 v[182:183], v[182:183], v[118:119]
	v_pk_mul_f32 v[184:185], v[184:185], v[112:113]
	v_pk_mul_f32 v[186:187], v[186:187], v[114:115]
	v_exp_f32_e32 v188, v180
	v_exp_f32_e32 v189, v181
	v_exp_f32_e32 v190, v182
	v_exp_f32_e32 v191, v183
	v_exp_f32_e32 v192, v184
	v_exp_f32_e32 v193, v185
	v_exp_f32_e32 v194, v186
	v_exp_f32_e32 v195, v187
	v_pk_add_f32 v[188:189], v[188:189], v[196:197] op_sel_hi:[1,0]
; __device__ __forceinline__ unsigned cvt_pk_bf16(float lo, float hi) { unsigned r; asm volatile("v_cvt_pk_bf16_f32 %0, %1, %2" : "=v"(r) : "v"(lo), "v"(hi)); return r; }
; __device__ __forceinline__ float gelu_tanh(float x) {
;     const float u = x * (0.7978845608f + 0.0356774081f * x * x);
;     const float e = __builtin_amdgcn_exp2f(u * 2.8853900818f);
;     return x - x * __builtin_amdgcn_rcpf(e + 1.0f);
;     __device__ __forceinline__ void operator()(const f32x4 (&acc)[2][2][4][2], const Unit& u, int wr, int wc, int fr, int fq) const {
;     ...
;             for (int m = 0; m < 4; ++m) { const int row = row0 + ai * HALF + m * 16; bf16_t* rowp = O + (size_t)row * ldc + col0; float s = 0.f, q = 0.f;
;                 const float rstd = rsv[ai][m];
; #pragma unroll
;                 for (int bj = 0; bj < 2; ++bj) { f32x4 v0 = acc[ai][bj][m][0] * rstd + bv[bj][0], v1 = acc[ai][bj][m][1] * rstd + bv[bj][1];
;                     if (ACT == 1) {
; #pragma unroll
;                         for (int e = 0; e < 4; ++e) { const float a = fmaxf(v0[e], 0.f), b2 = fmaxf(v1[e], 0.f); v0[e] = a * a; v1[e] = b2 * b2; } }
;                     if (ACT == 2) {
; #pragma unroll
;                         for (int e = 0; e < 4; ++e) { v0[e] = gelu_tanh(v0[e]); v1[e] = gelu_tanh(v1[e]); s += v0[e] + v1[e]; q += v0[e] * v0[e] + v1[e] * v1[e]; } }
;                     u32x4 w; w.x = cvt_pk_bf16(v0[0], v0[1]); w.y = cvt_pk_bf16(v0[2], v0[3]); w.z = cvt_pk_bf16(v1[0], v1[1]); w.w = cvt_pk_bf16(v1[2], v1[3]);
;                     *(u32x4*)(rowp + bj * HALF) = w; }
	v_pk_add_f32 v[190:191], v[190:191], v[196:197] op_sel_hi:[1,0]
	v_pk_add_f32 v[192:193], v[192:193], v[196:197] op_sel_hi:[1,0]
	v_pk_add_f32 v[194:195], v[194:195], v[196:197] op_sel_hi:[1,0]
	v_rcp_f32_e32 v188, v188
	v_rcp_f32_e32 v189, v189
	v_rcp_f32_e32 v190, v190
	v_rcp_f32_e32 v191, v191
	v_rcp_f32_e32 v192, v192
	v_rcp_f32_e32 v193, v193
	v_rcp_f32_e32 v194, v194
	v_rcp_f32_e32 v195, v195
	s_nop 0
	v_pk_fma_f32 v[116:117], v[116:117], v[188:189], v[116:117] neg_lo:[1,0,0] neg_hi:[1,0,0]
	v_pk_fma_f32 v[118:119], v[118:119], v[190:191], v[118:119] neg_lo:[1,0,0] neg_hi:[1,0,0]
	v_pk_fma_f32 v[112:113], v[112:113], v[192:193], v[112:113] neg_lo:[1,0,0] neg_hi:[1,0,0]
	v_pk_fma_f32 v[114:115], v[114:115], v[194:195], v[114:115] neg_lo:[1,0,0] neg_hi:[1,0,0]
	v_cvt_pk_bf16_f32 v164, v116, v117
	v_cvt_pk_bf16_f32 v165, v118, v119
	v_cvt_pk_bf16_f32 v166, v112, v113
	v_cvt_pk_bf16_f32 v167, v114, v115
	global_store_dwordx4 v[208:209], v[164:167], off offset:256 sc1
	v_pk_fma_f32 v[108:109], v[108:109], v[148:149], v[32:33] op_sel_hi:[1,0,1]
	v_pk_fma_f32 v[110:111], v[110:111], v[148:149], v[34:35] op_sel_hi:[1,0,1]
	v_pk_fma_f32 v[104:105], v[104:105], v[148:149], v[36:37] op_sel_hi:[1,0,1]
	v_pk_fma_f32 v[106:107], v[106:107], v[148:149], v[38:39] op_sel_hi:[1,0,1]
	v_lshl_add_u64 v[208:209], v[208:209], 0, s[42:43]
	v_pk_mul_f32 v[180:181], v[108:109], v[108:109]
	v_pk_mul_f32 v[182:183], v[110:111], v[110:111]
	v_pk_mul_f32 v[184:185], v[104:105], v[104:105]
	v_pk_mul_f32 v[186:187], v[106:107], v[106:107]
	v_pk_fma_f32 v[180:181], v[180:181], v[200:201], v[206:207] op_sel_hi:[1,0,0]
	v_pk_fma_f32 v[182:183], v[182:183], v[200:201], v[206:207] op_sel_hi:[1,0,0]
	v_pk_fma_f32 v[184:185], v[184:185], v[200:201], v[206:207] op_sel_hi:[1,0,0]
	v_pk_fma_f32 v[186:187], v[186:187], v[200:201], v[206:207] op_sel_hi:[1,0,0]
	v_pk_mul_f32 v[180:181], v[180:181], v[108:109]
	v_pk_mul_f32 v[182:183], v[182:183], v[110:111]
	v_pk_mul_f32 v[184:185], v[184:185], v[104:105]
	v_pk_mul_f32 v[186:187], v[186:187], v[106:107]
	v_exp_f32_e32 v188, v180
	v_exp_f32_e32 v189, v181
	v_exp_f32_e32 v190, v182
	v_exp_f32_e32 v191, v183
	v_exp_f32_e32 v192, v184
	v_exp_f32_e32 v193, v185
	v_exp_f32_e32 v194, v186
	v_exp_f32_e32 v195, v187
	v_pk_add_f32 v[188:189], v[188:189], v[196:197] op_sel_hi:[1,0]
	v_pk_add_f32 v[190:191], v[190:191], v[196:197] op_sel_hi:[1,0]
	v_pk_add_f32 v[192:193], v[192:193], v[196:197] op_sel_hi:[1,0]
	v_pk_add_f32 v[194:195], v[194:195], v[196:197] op_sel_hi:[1,0]
	v_rcp_f32_e32 v188, v188
	v_rcp_f32_e32 v189, v189
	v_rcp_f32_e32 v190, v190
	v_rcp_f32_e32 v191, v191
	v_rcp_f32_e32 v192, v192
	v_rcp_f32_e32 v193, v193
	v_rcp_f32_e32 v194, v194
	v_rcp_f32_e32 v195, v195
	s_nop 0
	v_pk_fma_f32 v[108:109], v[108:109], v[188:189], v[108:109] neg_lo:[1,0,0] neg_hi:[1,0,0]
	v_pk_fma_f32 v[110:111], v[110:111], v[190:191], v[110:111] neg_lo:[1,0,0] neg_hi:[1,0,0]
	v_pk_fma_f32 v[104:105], v[104:105], v[192:193], v[104:105] neg_lo:[1,0,0] neg_hi:[1,0,0]
	v_pk_fma_f32 v[106:107], v[106:107], v[194:195], v[106:107] neg_lo:[1,0,0] neg_hi:[1,0,0]
	v_cvt_pk_bf16_f32 v160, v108, v109
	v_cvt_pk_bf16_f32 v161, v110, v111
	v_cvt_pk_bf16_f32 v162, v104, v105
	v_cvt_pk_bf16_f32 v163, v106, v107
	global_store_dwordx4 v[208:209], v[160:163], off sc1
	v_pk_fma_f32 v[100:101], v[100:101], v[148:149], v[40:41] op_sel_hi:[1,0,1]
	v_pk_fma_f32 v[102:103], v[102:103], v[148:149], v[42:43] op_sel_hi:[1,0,1]
	v_pk_fma_f32 v[96:97], v[96:97], v[148:149], v[44:45] op_sel_hi:[1,0,1]
	v_pk_fma_f32 v[98:99], v[98:99], v[148:149], v[46:47] op_sel_hi:[1,0,1]
	v_pk_mul_f32 v[180:181], v[100:101], v[100:101]
	v_pk_mul_f32 v[182:183], v[102:103], v[102:103]
	v_pk_mul_f32 v[184:185], v[96:97], v[96:97]
	v_pk_mul_f32 v[186:187], v[98:99], v[98:99]
	v_pk_fma_f32 v[180:181], v[180:181], v[200:201], v[206:207] op_sel_hi:[1,0,0]
	v_pk_fma_f32 v[182:183], v[182:183], v[200:201], v[206:207] op_sel_hi:[1,0,0]
	v_pk_fma_f32 v[184:185], v[184:185], v[200:201], v[206:207] op_sel_hi:[1,0,0]
	v_pk_fma_f32 v[186:187], v[186:187], v[200:201], v[206:207] op_sel_hi:[1,0,0]
	v_pk_mul_f32 v[180:181], v[180:181], v[100:101]
	v_pk_mul_f32 v[182:183], v[182:183], v[102:103]
	v_pk_mul_f32 v[184:185], v[184:185], v[96:97]
	v_pk_mul_f32 v[186:187], v[186:187], v[98:99]
	v_exp_f32_e32 v188, v180
	v_exp_f32_e32 v189, v181
	v_exp_f32_e32 v190, v182
	v_exp_f32_e32 v191, v183
	v_exp_f32_e32 v192, v184
	v_exp_f32_e32 v193, v185
	v_exp_f32_e32 v194, v186
	v_exp_f32_e32 v195, v187
	v_pk_add_f32 v[188:189], v[188:189], v[196:197] op_sel_hi:[1,0]
	v_pk_add_f32 v[190:191], v[190:191], v[196:197] op_sel_hi:[1,0]
	v_pk_add_f32 v[192:193], v[192:193], v[196:197] op_sel_hi:[1,0]
	v_pk_add_f32 v[194:195], v[194:195], v[196:197] op_sel_hi:[1,0]
	v_rcp_f32_e32 v188, v188
	v_rcp_f32_e32 v189, v189
	v_rcp_f32_e32 v190, v190
	v_rcp_f32_e32 v191, v191
	v_rcp_f32_e32 v192, v192
	v_rcp_f32_e32 v193, v193
	v_rcp_f32_e32 v194, v194
	v_rcp_f32_e32 v195, v195
	s_nop 0
	v_pk_fma_f32 v[100:101], v[100:101], v[188:189], v[100:101] neg_lo:[1,0,0] neg_hi:[1,0,0]
	v_pk_fma_f32 v[102:103], v[102:103], v[190:191], v[102:103] neg_lo:[1,0,0] neg_hi:[1,0,0]
	v_pk_fma_f32 v[96:97], v[96:97], v[192:193], v[96:97] neg_lo:[1,0,0] neg_hi:[1,0,0]
	v_pk_fma_f32 v[98:99], v[98:99], v[194:195], v[98:99] neg_lo:[1,0,0] neg_hi:[1,0,0]
	v_cvt_pk_bf16_f32 v164, v100, v101
	v_cvt_pk_bf16_f32 v165, v102, v103
	v_cvt_pk_bf16_f32 v166, v96, v97
	v_cvt_pk_bf16_f32 v167, v98, v99
	global_store_dwordx4 v[208:209], v[164:167], off offset:256 sc1
	v_pk_fma_f32 v[92:93], v[92:93], v[150:151], v[32:33] op_sel_hi:[1,0,1]
; __device__ __forceinline__ unsigned cvt_pk_bf16(float lo, float hi) { unsigned r; asm volatile("v_cvt_pk_bf16_f32 %0, %1, %2" : "=v"(r) : "v"(lo), "v"(hi)); return r; }
; __device__ __forceinline__ float gelu_tanh(float x) {
;     const float u = x * (0.7978845608f + 0.0356774081f * x * x);
;     const float e = __builtin_amdgcn_exp2f(u * 2.8853900818f);
;     return x - x * __builtin_amdgcn_rcpf(e + 1.0f);
;     __device__ __forceinline__ void operator()(const f32x4 (&acc)[2][2][4][2], const Unit& u, int wr, int wc, int fr, int fq) const {
;     ...
;             for (int m = 0; m < 4; ++m) { const int row = row0 + ai * HALF + m * 16; bf16_t* rowp = O + (size_t)row * ldc + col0; float s = 0.f, q = 0.f;
;                 const float rstd = rsv[ai][m];
; #pragma unroll
;                 for (int bj = 0; bj < 2; ++bj) { f32x4 v0 = acc[ai][bj][m][0] * rstd + bv[bj][0], v1 = acc[ai][bj][m][1] * rstd + bv[bj][1];
;                     if (ACT == 1) {
; #pragma unroll
;                         for (int e = 0; e < 4; ++e) { const float a = fmaxf(v0[e], 0.f), b2 = fmaxf(v1[e], 0.f); v0[e] = a * a; v1[e] = b2 * b2; } }
;                     if (ACT == 2) {
; #pragma unroll
;                         for (int e = 0; e < 4; ++e) { v0[e] = gelu_tanh(v0[e]); v1[e] = gelu_tanh(v1[e]); s += v0[e] + v1[e]; q += v0[e] * v0[e] + v1[e] * v1[e]; } }
;                     u32x4 w; w.x = cvt_pk_bf16(v0[0], v0[1]); w.y = cvt_pk_bf16(v0[2], v0[3]); w.z = cvt_pk_bf16(v1[0], v1[1]); w.w = cvt_pk_bf16(v1[2], v1[3]);
;                     *(u32x4*)(rowp + bj * HALF) = w; }
	v_pk_fma_f32 v[94:95], v[94:95], v[150:151], v[34:35] op_sel_hi:[1,0,1]
	v_pk_fma_f32 v[88:89], v[88:89], v[150:151], v[36:37] op_sel_hi:[1,0,1]
	v_pk_fma_f32 v[90:91], v[90:91], v[150:151], v[38:39] op_sel_hi:[1,0,1]
	v_lshl_add_u64 v[208:209], v[208:209], 0, s[42:43]
	v_pk_mul_f32 v[180:181], v[92:93], v[92:93]
	v_pk_mul_f32 v[182:183], v[94:95], v[94:95]
	v_pk_mul_f32 v[184:185], v[88:89], v[88:89]
	v_pk_mul_f32 v[186:187], v[90:91], v[90:91]
	v_pk_fma_f32 v[180:181], v[180:181], v[200:201], v[206:207] op_sel_hi:[1,0,0]
	v_pk_fma_f32 v[182:183], v[182:183], v[200:201], v[206:207] op_sel_hi:[1,0,0]
	v_pk_fma_f32 v[184:185], v[184:185], v[200:201], v[206:207] op_sel_hi:[1,0,0]
	v_pk_fma_f32 v[186:187], v[186:187], v[200:201], v[206:207] op_sel_hi:[1,0,0]
	v_pk_mul_f32 v[180:181], v[180:181], v[92:93]
	v_pk_mul_f32 v[182:183], v[182:183], v[94:95]
	v_pk_mul_f32 v[184:185], v[184:185], v[88:89]
	v_pk_mul_f32 v[186:187], v[186:187], v[90:91]
	v_exp_f32_e32 v188, v180
	v_exp_f32_e32 v189, v181
	v_exp_f32_e32 v190, v182
	v_exp_f32_e32 v191, v183
	v_exp_f32_e32 v192, v184
	v_exp_f32_e32 v193, v185
	v_exp_f32_e32 v194, v186
	v_exp_f32_e32 v195, v187
	v_pk_add_f32 v[188:189], v[188:189], v[196:197] op_sel_hi:[1,0]
	v_pk_add_f32 v[190:191], v[190:191], v[196:197] op_sel_hi:[1,0]
	v_pk_add_f32 v[192:193], v[192:193], v[196:197] op_sel_hi:[1,0]
	v_pk_add_f32 v[194:195], v[194:195], v[196:197] op_sel_hi:[1,0]
	v_rcp_f32_e32 v188, v188
	v_rcp_f32_e32 v189, v189
	v_rcp_f32_e32 v190, v190
	v_rcp_f32_e32 v191, v191
	v_rcp_f32_e32 v192, v192
	v_rcp_f32_e32 v193, v193
	v_rcp_f32_e32 v194, v194
	v_rcp_f32_e32 v195, v195
	s_nop 0
	v_pk_fma_f32 v[92:93], v[92:93], v[188:189], v[92:93] neg_lo:[1,0,0] neg_hi:[1,0,0]
	v_pk_fma_f32 v[94:95], v[94:95], v[190:191], v[94:95] neg_lo:[1,0,0] neg_hi:[1,0,0]
	v_pk_fma_f32 v[88:89], v[88:89], v[192:193], v[88:89] neg_lo:[1,0,0] neg_hi:[1,0,0]
	v_pk_fma_f32 v[90:91], v[90:91], v[194:195], v[90:91] neg_lo:[1,0,0] neg_hi:[1,0,0]
	v_cvt_pk_bf16_f32 v160, v92, v93
	v_cvt_pk_bf16_f32 v161, v94, v95
	v_cvt_pk_bf16_f32 v162, v88, v89
	v_cvt_pk_bf16_f32 v163, v90, v91
	global_store_dwordx4 v[208:209], v[160:163], off sc1
	v_pk_fma_f32 v[84:85], v[84:85], v[150:151], v[40:41] op_sel_hi:[1,0,1]
	v_pk_fma_f32 v[86:87], v[86:87], v[150:151], v[42:43] op_sel_hi:[1,0,1]
	v_pk_fma_f32 v[80:81], v[80:81], v[150:151], v[44:45] op_sel_hi:[1,0,1]
	v_pk_fma_f32 v[82:83], v[82:83], v[150:151], v[46:47] op_sel_hi:[1,0,1]
	v_pk_mul_f32 v[180:181], v[84:85], v[84:85]
	v_pk_mul_f32 v[182:183], v[86:87], v[86:87]
	v_pk_mul_f32 v[184:185], v[80:81], v[80:81]
	v_pk_mul_f32 v[186:187], v[82:83], v[82:83]
	v_pk_fma_f32 v[180:181], v[180:181], v[200:201], v[206:207] op_sel_hi:[1,0,0]
	v_pk_fma_f32 v[182:183], v[182:183], v[200:201], v[206:207] op_sel_hi:[1,0,0]
	v_pk_fma_f32 v[184:185], v[184:185], v[200:201], v[206:207] op_sel_hi:[1,0,0]
	v_pk_fma_f32 v[186:187], v[186:187], v[200:201], v[206:207] op_sel_hi:[1,0,0]
	v_pk_mul_f32 v[180:181], v[180:181], v[84:85]
	v_pk_mul_f32 v[182:183], v[182:183], v[86:87]
	v_pk_mul_f32 v[184:185], v[184:185], v[80:81]
	v_pk_mul_f32 v[186:187], v[186:187], v[82:83]
	v_exp_f32_e32 v188, v180
	v_exp_f32_e32 v189, v181
	v_exp_f32_e32 v190, v182
	v_exp_f32_e32 v191, v183
	v_exp_f32_e32 v192, v184
	v_exp_f32_e32 v193, v185
	v_exp_f32_e32 v194, v186
	v_exp_f32_e32 v195, v187
	v_pk_add_f32 v[188:189], v[188:189], v[196:197] op_sel_hi:[1,0]
	v_pk_add_f32 v[190:191], v[190:191], v[196:197] op_sel_hi:[1,0]
	v_pk_add_f32 v[192:193], v[192:193], v[196:197] op_sel_hi:[1,0]
	v_pk_add_f32 v[194:195], v[194:195], v[196:197] op_sel_hi:[1,0]
	v_rcp_f32_e32 v188, v188
	v_rcp_f32_e32 v189, v189
	v_rcp_f32_e32 v190, v190
	v_rcp_f32_e32 v191, v191
	v_rcp_f32_e32 v192, v192
	v_rcp_f32_e32 v193, v193
	v_rcp_f32_e32 v194, v194
	v_rcp_f32_e32 v195, v195
	s_nop 0
	v_pk_fma_f32 v[84:85], v[84:85], v[188:189], v[84:85] neg_lo:[1,0,0] neg_hi:[1,0,0]
	v_pk_fma_f32 v[86:87], v[86:87], v[190:191], v[86:87] neg_lo:[1,0,0] neg_hi:[1,0,0]
	v_pk_fma_f32 v[80:81], v[80:81], v[192:193], v[80:81] neg_lo:[1,0,0] neg_hi:[1,0,0]
	v_pk_fma_f32 v[82:83], v[82:83], v[194:195], v[82:83] neg_lo:[1,0,0] neg_hi:[1,0,0]
	v_cvt_pk_bf16_f32 v164, v84, v85
	v_cvt_pk_bf16_f32 v165, v86, v87
	v_cvt_pk_bf16_f32 v166, v80, v81
	v_cvt_pk_bf16_f32 v167, v82, v83
	global_store_dwordx4 v[208:209], v[164:167], off offset:256 sc1
	v_pk_fma_f32 v[76:77], v[76:77], v[152:153], v[32:33] op_sel_hi:[1,0,1]
	v_pk_fma_f32 v[78:79], v[78:79], v[152:153], v[34:35] op_sel_hi:[1,0,1]
	v_pk_fma_f32 v[72:73], v[72:73], v[152:153], v[36:37] op_sel_hi:[1,0,1]
	v_pk_fma_f32 v[74:75], v[74:75], v[152:153], v[38:39] op_sel_hi:[1,0,1]
	s_mov_b64 s[16:17], 0xa0000
	v_lshl_add_u64 v[208:209], v[208:209], 0, s[16:17]
	v_pk_mul_f32 v[180:181], v[76:77], v[76:77]
	v_pk_mul_f32 v[182:183], v[78:79], v[78:79]
	v_pk_mul_f32 v[184:185], v[72:73], v[72:73]
	v_pk_mul_f32 v[186:187], v[74:75], v[74:75]
	v_pk_fma_f32 v[180:181], v[180:181], v[200:201], v[206:207] op_sel_hi:[1,0,0]
	v_pk_fma_f32 v[182:183], v[182:183], v[200:201], v[206:207] op_sel_hi:[1,0,0]
	v_pk_fma_f32 v[184:185], v[184:185], v[200:201], v[206:207] op_sel_hi:[1,0,0]
	v_pk_fma_f32 v[186:187], v[186:187], v[200:201], v[206:207] op_sel_hi:[1,0,0]
	v_pk_mul_f32 v[180:181], v[180:181], v[76:77]
	v_pk_mul_f32 v[182:183], v[182:183], v[78:79]
	v_pk_mul_f32 v[184:185], v[184:185], v[72:73]
	v_pk_mul_f32 v[186:187], v[186:187], v[74:75]
	v_exp_f32_e32 v188, v180
	v_exp_f32_e32 v189, v181
	v_exp_f32_e32 v190, v182
	v_exp_f32_e32 v191, v183
	v_exp_f32_e32 v192, v184
	v_exp_f32_e32 v193, v185
	v_exp_f32_e32 v194, v186
	v_exp_f32_e32 v195, v187
; __device__ __forceinline__ unsigned cvt_pk_bf16(float lo, float hi) { unsigned r; asm volatile("v_cvt_pk_bf16_f32 %0, %1, %2" : "=v"(r) : "v"(lo), "v"(hi)); return r; }
; __device__ __forceinline__ float gelu_tanh(float x) {
;     const float u = x * (0.7978845608f + 0.0356774081f * x * x);
;     const float e = __builtin_amdgcn_exp2f(u * 2.8853900818f);
;     return x - x * __builtin_amdgcn_rcpf(e + 1.0f);
;     __device__ __forceinline__ void operator()(const f32x4 (&acc)[2][2][4][2], const Unit& u, int wr, int wc, int fr, int fq) const {
;     ...
;             for (int m = 0; m < 4; ++m) { const int row = row0 + ai * HALF + m * 16; bf16_t* rowp = O + (size_t)row * ldc + col0; float s = 0.f, q = 0.f;
;                 const float rstd = rsv[ai][m];
; #pragma unroll
;                 for (int bj = 0; bj < 2; ++bj) { f32x4 v0 = acc[ai][bj][m][0] * rstd + bv[bj][0], v1 = acc[ai][bj][m][1] * rstd + bv[bj][1];
;                     if (ACT == 1) {
; #pragma unroll
;                         for (int e = 0; e < 4; ++e) { const float a = fmaxf(v0[e], 0.f), b2 = fmaxf(v1[e], 0.f); v0[e] = a * a; v1[e] = b2 * b2; } }
;                     if (ACT == 2) {
; #pragma unroll
;                         for (int e = 0; e < 4; ++e) { v0[e] = gelu_tanh(v0[e]); v1[e] = gelu_tanh(v1[e]); s += v0[e] + v1[e]; q += v0[e] * v0[e] + v1[e] * v1[e]; } }
;                     u32x4 w; w.x = cvt_pk_bf16(v0[0], v0[1]); w.y = cvt_pk_bf16(v0[2], v0[3]); w.z = cvt_pk_bf16(v1[0], v1[1]); w.w = cvt_pk_bf16(v1[2], v1[3]);
;                     *(u32x4*)(rowp + bj * HALF) = w; }
	v_pk_add_f32 v[188:189], v[188:189], v[196:197] op_sel_hi:[1,0]
	v_pk_add_f32 v[190:191], v[190:191], v[196:197] op_sel_hi:[1,0]
	v_pk_add_f32 v[192:193], v[192:193], v[196:197] op_sel_hi:[1,0]
	v_pk_add_f32 v[194:195], v[194:195], v[196:197] op_sel_hi:[1,0]
	v_rcp_f32_e32 v188, v188
	v_rcp_f32_e32 v189, v189
	v_rcp_f32_e32 v190, v190
	v_rcp_f32_e32 v191, v191
	v_rcp_f32_e32 v192, v192
	v_rcp_f32_e32 v193, v193
	v_rcp_f32_e32 v194, v194
	v_rcp_f32_e32 v195, v195
	s_nop 0
	v_pk_fma_f32 v[76:77], v[76:77], v[188:189], v[76:77] neg_lo:[1,0,0] neg_hi:[1,0,0]
	v_pk_fma_f32 v[78:79], v[78:79], v[190:191], v[78:79] neg_lo:[1,0,0] neg_hi:[1,0,0]
	v_pk_fma_f32 v[72:73], v[72:73], v[192:193], v[72:73] neg_lo:[1,0,0] neg_hi:[1,0,0]
	v_pk_fma_f32 v[74:75], v[74:75], v[194:195], v[74:75] neg_lo:[1,0,0] neg_hi:[1,0,0]
	v_cvt_pk_bf16_f32 v160, v76, v77
	v_cvt_pk_bf16_f32 v161, v78, v79
	v_cvt_pk_bf16_f32 v162, v72, v73
	v_cvt_pk_bf16_f32 v163, v74, v75
	global_store_dwordx4 v[208:209], v[160:163], off sc1
	v_pk_fma_f32 v[68:69], v[68:69], v[152:153], v[40:41] op_sel_hi:[1,0,1]
	v_pk_fma_f32 v[70:71], v[70:71], v[152:153], v[42:43] op_sel_hi:[1,0,1]
	v_pk_fma_f32 v[64:65], v[64:65], v[152:153], v[44:45] op_sel_hi:[1,0,1]
	v_pk_fma_f32 v[66:67], v[66:67], v[152:153], v[46:47] op_sel_hi:[1,0,1]
	v_pk_mul_f32 v[180:181], v[68:69], v[68:69]
	v_pk_mul_f32 v[182:183], v[70:71], v[70:71]
	v_pk_mul_f32 v[184:185], v[64:65], v[64:65]
	v_pk_mul_f32 v[186:187], v[66:67], v[66:67]
	v_pk_fma_f32 v[180:181], v[180:181], v[200:201], v[206:207] op_sel_hi:[1,0,0]
	v_pk_fma_f32 v[182:183], v[182:183], v[200:201], v[206:207] op_sel_hi:[1,0,0]
	v_pk_fma_f32 v[184:185], v[184:185], v[200:201], v[206:207] op_sel_hi:[1,0,0]
	v_pk_fma_f32 v[186:187], v[186:187], v[200:201], v[206:207] op_sel_hi:[1,0,0]
	v_pk_mul_f32 v[180:181], v[180:181], v[68:69]
	v_pk_mul_f32 v[182:183], v[182:183], v[70:71]
	v_pk_mul_f32 v[184:185], v[184:185], v[64:65]
	v_pk_mul_f32 v[186:187], v[186:187], v[66:67]
	v_exp_f32_e32 v188, v180
	v_exp_f32_e32 v189, v181
	v_exp_f32_e32 v190, v182
	v_exp_f32_e32 v191, v183
	v_exp_f32_e32 v192, v184
	v_exp_f32_e32 v193, v185
	v_exp_f32_e32 v194, v186
	v_exp_f32_e32 v195, v187
	v_pk_add_f32 v[188:189], v[188:189], v[196:197] op_sel_hi:[1,0]
	v_pk_add_f32 v[190:191], v[190:191], v[196:197] op_sel_hi:[1,0]
	v_pk_add_f32 v[192:193], v[192:193], v[196:197] op_sel_hi:[1,0]
	v_pk_add_f32 v[194:195], v[194:195], v[196:197] op_sel_hi:[1,0]
	v_rcp_f32_e32 v188, v188
	v_rcp_f32_e32 v189, v189
	v_rcp_f32_e32 v190, v190
	v_rcp_f32_e32 v191, v191
	v_rcp_f32_e32 v192, v192
	v_rcp_f32_e32 v193, v193
	v_rcp_f32_e32 v194, v194
	v_rcp_f32_e32 v195, v195
	s_nop 0
	v_pk_fma_f32 v[68:69], v[68:69], v[188:189], v[68:69] neg_lo:[1,0,0] neg_hi:[1,0,0]
	v_pk_fma_f32 v[70:71], v[70:71], v[190:191], v[70:71] neg_lo:[1,0,0] neg_hi:[1,0,0]
	v_pk_fma_f32 v[64:65], v[64:65], v[192:193], v[64:65] neg_lo:[1,0,0] neg_hi:[1,0,0]
	v_pk_fma_f32 v[66:67], v[66:67], v[194:195], v[66:67] neg_lo:[1,0,0] neg_hi:[1,0,0]
	v_cvt_pk_bf16_f32 v164, v68, v69
	v_cvt_pk_bf16_f32 v165, v70, v71
	v_cvt_pk_bf16_f32 v166, v64, v65
	v_cvt_pk_bf16_f32 v167, v66, v67
	global_store_dwordx4 v[208:209], v[164:167], off offset:256 sc1
	v_pk_fma_f32 v[60:61], v[60:61], v[154:155], v[32:33] op_sel_hi:[1,0,1]
	v_pk_fma_f32 v[62:63], v[62:63], v[154:155], v[34:35] op_sel_hi:[1,0,1]
	v_pk_fma_f32 v[56:57], v[56:57], v[154:155], v[36:37] op_sel_hi:[1,0,1]
	v_pk_fma_f32 v[58:59], v[58:59], v[154:155], v[38:39] op_sel_hi:[1,0,1]
	v_lshl_add_u64 v[208:209], v[208:209], 0, s[42:43]
	v_pk_mul_f32 v[180:181], v[60:61], v[60:61]
	v_pk_mul_f32 v[182:183], v[62:63], v[62:63]
	v_pk_mul_f32 v[184:185], v[56:57], v[56:57]
	v_pk_mul_f32 v[186:187], v[58:59], v[58:59]
	v_pk_fma_f32 v[180:181], v[180:181], v[200:201], v[206:207] op_sel_hi:[1,0,0]
	v_pk_fma_f32 v[182:183], v[182:183], v[200:201], v[206:207] op_sel_hi:[1,0,0]
	v_pk_fma_f32 v[184:185], v[184:185], v[200:201], v[206:207] op_sel_hi:[1,0,0]
	v_pk_fma_f32 v[186:187], v[186:187], v[200:201], v[206:207] op_sel_hi:[1,0,0]
	v_pk_mul_f32 v[180:181], v[180:181], v[60:61]
	v_pk_mul_f32 v[182:183], v[182:183], v[62:63]
	v_pk_mul_f32 v[184:185], v[184:185], v[56:57]
	v_pk_mul_f32 v[186:187], v[186:187], v[58:59]
	v_exp_f32_e32 v188, v180
	v_exp_f32_e32 v189, v181
	v_exp_f32_e32 v190, v182
	v_exp_f32_e32 v191, v183
	v_exp_f32_e32 v192, v184
	v_exp_f32_e32 v193, v185
	v_exp_f32_e32 v194, v186
	v_exp_f32_e32 v195, v187
	v_pk_add_f32 v[188:189], v[188:189], v[196:197] op_sel_hi:[1,0]
	v_pk_add_f32 v[190:191], v[190:191], v[196:197] op_sel_hi:[1,0]
	v_pk_add_f32 v[192:193], v[192:193], v[196:197] op_sel_hi:[1,0]
	v_pk_add_f32 v[194:195], v[194:195], v[196:197] op_sel_hi:[1,0]
	v_rcp_f32_e32 v188, v188
	v_rcp_f32_e32 v189, v189
	v_rcp_f32_e32 v190, v190
	v_rcp_f32_e32 v191, v191
	v_rcp_f32_e32 v192, v192
	v_rcp_f32_e32 v193, v193
	v_rcp_f32_e32 v194, v194
	v_rcp_f32_e32 v195, v195
	s_nop 0
	v_pk_fma_f32 v[60:61], v[60:61], v[188:189], v[60:61] neg_lo:[1,0,0] neg_hi:[1,0,0]
	v_pk_fma_f32 v[62:63], v[62:63], v[190:191], v[62:63] neg_lo:[1,0,0] neg_hi:[1,0,0]
	v_pk_fma_f32 v[56:57], v[56:57], v[192:193], v[56:57] neg_lo:[1,0,0] neg_hi:[1,0,0]
	v_pk_fma_f32 v[58:59], v[58:59], v[194:195], v[58:59] neg_lo:[1,0,0] neg_hi:[1,0,0]
	v_cvt_pk_bf16_f32 v160, v60, v61
	v_cvt_pk_bf16_f32 v161, v62, v63
	v_cvt_pk_bf16_f32 v162, v56, v57
	v_cvt_pk_bf16_f32 v163, v58, v59
	global_store_dwordx4 v[208:209], v[160:163], off sc1
	v_pk_fma_f32 v[52:53], v[52:53], v[154:155], v[40:41] op_sel_hi:[1,0,1]
	v_pk_fma_f32 v[54:55], v[54:55], v[154:155], v[42:43] op_sel_hi:[1,0,1]
	v_pk_fma_f32 v[48:49], v[48:49], v[154:155], v[44:45] op_sel_hi:[1,0,1]
; __device__ __forceinline__ unsigned cvt_pk_bf16(float lo, float hi) { unsigned r; asm volatile("v_cvt_pk_bf16_f32 %0, %1, %2" : "=v"(r) : "v"(lo), "v"(hi)); return r; }
; __device__ __forceinline__ float gelu_tanh(float x) {
;     const float u = x * (0.7978845608f + 0.0356774081f * x * x);
;     const float e = __builtin_amdgcn_exp2f(u * 2.8853900818f);
;     return x - x * __builtin_amdgcn_rcpf(e + 1.0f);
;     __device__ __forceinline__ void operator()(const f32x4 (&acc)[2][2][4][2], const Unit& u, int wr, int wc, int fr, int fq) const {
;     ...
;             for (int m = 0; m < 4; ++m) { const int row = row0 + ai * HALF + m * 16; bf16_t* rowp = O + (size_t)row * ldc + col0; float s = 0.f, q = 0.f;
;                 const float rstd = rsv[ai][m];
; #pragma unroll
;                 for (int bj = 0; bj < 2; ++bj) { f32x4 v0 = acc[ai][bj][m][0] * rstd + bv[bj][0], v1 = acc[ai][bj][m][1] * rstd + bv[bj][1];
;                     if (ACT == 1) {
; #pragma unroll
;                         for (int e = 0; e < 4; ++e) { const float a = fmaxf(v0[e], 0.f), b2 = fmaxf(v1[e], 0.f); v0[e] = a * a; v1[e] = b2 * b2; } }
;                     if (ACT == 2) {
; #pragma unroll
;                         for (int e = 0; e < 4; ++e) { v0[e] = gelu_tanh(v0[e]); v1[e] = gelu_tanh(v1[e]); s += v0[e] + v1[e]; q += v0[e] * v0[e] + v1[e] * v1[e]; } }
;                     u32x4 w; w.x = cvt_pk_bf16(v0[0], v0[1]); w.y = cvt_pk_bf16(v0[2], v0[3]); w.z = cvt_pk_bf16(v1[0], v1[1]); w.w = cvt_pk_bf16(v1[2], v1[3]);
;                     *(u32x4*)(rowp + bj * HALF) = w; }
	v_pk_fma_f32 v[50:51], v[50:51], v[154:155], v[46:47] op_sel_hi:[1,0,1]
	v_pk_mul_f32 v[180:181], v[52:53], v[52:53]
	v_pk_mul_f32 v[182:183], v[54:55], v[54:55]
	v_pk_mul_f32 v[184:185], v[48:49], v[48:49]
	v_pk_mul_f32 v[186:187], v[50:51], v[50:51]
	v_pk_fma_f32 v[180:181], v[180:181], v[200:201], v[206:207] op_sel_hi:[1,0,0]
	v_pk_fma_f32 v[182:183], v[182:183], v[200:201], v[206:207] op_sel_hi:[1,0,0]
	v_pk_fma_f32 v[184:185], v[184:185], v[200:201], v[206:207] op_sel_hi:[1,0,0]
	v_pk_fma_f32 v[186:187], v[186:187], v[200:201], v[206:207] op_sel_hi:[1,0,0]
	v_pk_mul_f32 v[180:181], v[180:181], v[52:53]
	v_pk_mul_f32 v[182:183], v[182:183], v[54:55]
	v_pk_mul_f32 v[184:185], v[184:185], v[48:49]
	v_pk_mul_f32 v[186:187], v[186:187], v[50:51]
	v_exp_f32_e32 v188, v180
	v_exp_f32_e32 v189, v181
	v_exp_f32_e32 v190, v182
	v_exp_f32_e32 v191, v183
	v_exp_f32_e32 v192, v184
	v_exp_f32_e32 v193, v185
	v_exp_f32_e32 v194, v186
	v_exp_f32_e32 v195, v187
	v_pk_add_f32 v[188:189], v[188:189], v[196:197] op_sel_hi:[1,0]
	v_pk_add_f32 v[190:191], v[190:191], v[196:197] op_sel_hi:[1,0]
	v_pk_add_f32 v[192:193], v[192:193], v[196:197] op_sel_hi:[1,0]
	v_pk_add_f32 v[194:195], v[194:195], v[196:197] op_sel_hi:[1,0]
	v_rcp_f32_e32 v188, v188
	v_rcp_f32_e32 v189, v189
	v_rcp_f32_e32 v190, v190
	v_rcp_f32_e32 v191, v191
	v_rcp_f32_e32 v192, v192
	v_rcp_f32_e32 v193, v193
	v_rcp_f32_e32 v194, v194
	v_rcp_f32_e32 v195, v195
	s_nop 0
	v_pk_fma_f32 v[52:53], v[52:53], v[188:189], v[52:53] neg_lo:[1,0,0] neg_hi:[1,0,0]
	v_pk_fma_f32 v[54:55], v[54:55], v[190:191], v[54:55] neg_lo:[1,0,0] neg_hi:[1,0,0]
	v_pk_fma_f32 v[48:49], v[48:49], v[192:193], v[48:49] neg_lo:[1,0,0] neg_hi:[1,0,0]
	v_pk_fma_f32 v[50:51], v[50:51], v[194:195], v[50:51] neg_lo:[1,0,0] neg_hi:[1,0,0]
	v_cvt_pk_bf16_f32 v164, v52, v53
	v_cvt_pk_bf16_f32 v165, v54, v55
	v_cvt_pk_bf16_f32 v166, v48, v49
	v_cvt_pk_bf16_f32 v167, v50, v51
	global_store_dwordx4 v[208:209], v[164:167], off offset:256 sc1
	v_pk_fma_f32 v[28:29], v[28:29], v[156:157], v[32:33] op_sel_hi:[1,0,1]
	v_pk_fma_f32 v[30:31], v[30:31], v[156:157], v[34:35] op_sel_hi:[1,0,1]
	v_pk_fma_f32 v[24:25], v[24:25], v[156:157], v[36:37] op_sel_hi:[1,0,1]
	v_pk_fma_f32 v[26:27], v[26:27], v[156:157], v[38:39] op_sel_hi:[1,0,1]
	v_lshl_add_u64 v[208:209], v[208:209], 0, s[42:43]
	v_pk_mul_f32 v[180:181], v[28:29], v[28:29]
	v_pk_mul_f32 v[182:183], v[30:31], v[30:31]
	v_pk_mul_f32 v[184:185], v[24:25], v[24:25]
	v_pk_mul_f32 v[186:187], v[26:27], v[26:27]
	v_pk_fma_f32 v[180:181], v[180:181], v[200:201], v[206:207] op_sel_hi:[1,0,0]
	v_pk_fma_f32 v[182:183], v[182:183], v[200:201], v[206:207] op_sel_hi:[1,0,0]
	v_pk_fma_f32 v[184:185], v[184:185], v[200:201], v[206:207] op_sel_hi:[1,0,0]
	v_pk_fma_f32 v[186:187], v[186:187], v[200:201], v[206:207] op_sel_hi:[1,0,0]
	v_pk_mul_f32 v[180:181], v[180:181], v[28:29]
	v_pk_mul_f32 v[182:183], v[182:183], v[30:31]
	v_pk_mul_f32 v[184:185], v[184:185], v[24:25]
	v_pk_mul_f32 v[186:187], v[186:187], v[26:27]
	v_exp_f32_e32 v188, v180
	v_exp_f32_e32 v189, v181
	v_exp_f32_e32 v190, v182
	v_exp_f32_e32 v191, v183
	v_exp_f32_e32 v192, v184
	v_exp_f32_e32 v193, v185
	v_exp_f32_e32 v194, v186
	v_exp_f32_e32 v195, v187
	v_pk_add_f32 v[188:189], v[188:189], v[196:197] op_sel_hi:[1,0]
	v_pk_add_f32 v[190:191], v[190:191], v[196:197] op_sel_hi:[1,0]
	v_pk_add_f32 v[192:193], v[192:193], v[196:197] op_sel_hi:[1,0]
	v_pk_add_f32 v[194:195], v[194:195], v[196:197] op_sel_hi:[1,0]
	v_rcp_f32_e32 v188, v188
	v_rcp_f32_e32 v189, v189
	v_rcp_f32_e32 v190, v190
	v_rcp_f32_e32 v191, v191
	v_rcp_f32_e32 v192, v192
	v_rcp_f32_e32 v193, v193
	v_rcp_f32_e32 v194, v194
	v_rcp_f32_e32 v195, v195
	s_nop 0
	v_pk_fma_f32 v[28:29], v[28:29], v[188:189], v[28:29] neg_lo:[1,0,0] neg_hi:[1,0,0]
	v_pk_fma_f32 v[30:31], v[30:31], v[190:191], v[30:31] neg_lo:[1,0,0] neg_hi:[1,0,0]
	v_pk_fma_f32 v[24:25], v[24:25], v[192:193], v[24:25] neg_lo:[1,0,0] neg_hi:[1,0,0]
	v_pk_fma_f32 v[26:27], v[26:27], v[194:195], v[26:27] neg_lo:[1,0,0] neg_hi:[1,0,0]
	v_cvt_pk_bf16_f32 v160, v28, v29
	v_cvt_pk_bf16_f32 v161, v30, v31
	v_cvt_pk_bf16_f32 v162, v24, v25
	v_cvt_pk_bf16_f32 v163, v26, v27
	global_store_dwordx4 v[208:209], v[160:163], off sc1
	v_pk_fma_f32 v[20:21], v[20:21], v[156:157], v[40:41] op_sel_hi:[1,0,1]
	v_pk_fma_f32 v[22:23], v[22:23], v[156:157], v[42:43] op_sel_hi:[1,0,1]
	v_pk_fma_f32 v[16:17], v[16:17], v[156:157], v[44:45] op_sel_hi:[1,0,1]
	v_pk_fma_f32 v[18:19], v[18:19], v[156:157], v[46:47] op_sel_hi:[1,0,1]
	v_pk_mul_f32 v[180:181], v[20:21], v[20:21]
	v_pk_mul_f32 v[182:183], v[22:23], v[22:23]
	v_pk_mul_f32 v[184:185], v[16:17], v[16:17]
	v_pk_mul_f32 v[186:187], v[18:19], v[18:19]
	v_pk_fma_f32 v[180:181], v[180:181], v[200:201], v[206:207] op_sel_hi:[1,0,0]
	v_pk_fma_f32 v[182:183], v[182:183], v[200:201], v[206:207] op_sel_hi:[1,0,0]
	v_pk_fma_f32 v[184:185], v[184:185], v[200:201], v[206:207] op_sel_hi:[1,0,0]
	v_pk_fma_f32 v[186:187], v[186:187], v[200:201], v[206:207] op_sel_hi:[1,0,0]
	v_pk_mul_f32 v[180:181], v[180:181], v[20:21]
	v_pk_mul_f32 v[182:183], v[182:183], v[22:23]
	v_pk_mul_f32 v[184:185], v[184:185], v[16:17]
	v_pk_mul_f32 v[186:187], v[186:187], v[18:19]
	v_exp_f32_e32 v188, v180
	v_exp_f32_e32 v189, v181
	v_exp_f32_e32 v190, v182
	v_exp_f32_e32 v191, v183
	v_exp_f32_e32 v192, v184
	v_exp_f32_e32 v193, v185
	v_exp_f32_e32 v194, v186
; __device__ __forceinline__ unsigned cvt_pk_bf16(float lo, float hi) { unsigned r; asm volatile("v_cvt_pk_bf16_f32 %0, %1, %2" : "=v"(r) : "v"(lo), "v"(hi)); return r; }
; __device__ __forceinline__ float gelu_tanh(float x) {
;     const float u = x * (0.7978845608f + 0.0356774081f * x * x);
;     const float e = __builtin_amdgcn_exp2f(u * 2.8853900818f);
;     return x - x * __builtin_amdgcn_rcpf(e + 1.0f);
;     __device__ __forceinline__ void operator()(const f32x4 (&acc)[2][2][4][2], const Unit& u, int wr, int wc, int fr, int fq) const {
;     ...
;             for (int m = 0; m < 4; ++m) { const int row = row0 + ai * HALF + m * 16; bf16_t* rowp = O + (size_t)row * ldc + col0; float s = 0.f, q = 0.f;
;                 const float rstd = rsv[ai][m];
; #pragma unroll
;                 for (int bj = 0; bj < 2; ++bj) { f32x4 v0 = acc[ai][bj][m][0] * rstd + bv[bj][0], v1 = acc[ai][bj][m][1] * rstd + bv[bj][1];
;                     if (ACT == 1) {
; #pragma unroll
;                         for (int e = 0; e < 4; ++e) { const float a = fmaxf(v0[e], 0.f), b2 = fmaxf(v1[e], 0.f); v0[e] = a * a; v1[e] = b2 * b2; } }
;                     if (ACT == 2) {
; #pragma unroll
;                         for (int e = 0; e < 4; ++e) { v0[e] = gelu_tanh(v0[e]); v1[e] = gelu_tanh(v1[e]); s += v0[e] + v1[e]; q += v0[e] * v0[e] + v1[e] * v1[e]; } }
;                     u32x4 w; w.x = cvt_pk_bf16(v0[0], v0[1]); w.y = cvt_pk_bf16(v0[2], v0[3]); w.z = cvt_pk_bf16(v1[0], v1[1]); w.w = cvt_pk_bf16(v1[2], v1[3]);
;                     *(u32x4*)(rowp + bj * HALF) = w; }
	v_exp_f32_e32 v195, v187
	v_pk_add_f32 v[188:189], v[188:189], v[196:197] op_sel_hi:[1,0]
	v_pk_add_f32 v[190:191], v[190:191], v[196:197] op_sel_hi:[1,0]
	v_pk_add_f32 v[192:193], v[192:193], v[196:197] op_sel_hi:[1,0]
	v_pk_add_f32 v[194:195], v[194:195], v[196:197] op_sel_hi:[1,0]
	v_rcp_f32_e32 v188, v188
	v_rcp_f32_e32 v189, v189
	v_rcp_f32_e32 v190, v190
	v_rcp_f32_e32 v191, v191
	v_rcp_f32_e32 v192, v192
	v_rcp_f32_e32 v193, v193
	v_rcp_f32_e32 v194, v194
	v_rcp_f32_e32 v195, v195
	s_nop 0
	v_pk_fma_f32 v[20:21], v[20:21], v[188:189], v[20:21] neg_lo:[1,0,0] neg_hi:[1,0,0]
	v_pk_fma_f32 v[22:23], v[22:23], v[190:191], v[22:23] neg_lo:[1,0,0] neg_hi:[1,0,0]
	v_pk_fma_f32 v[16:17], v[16:17], v[192:193], v[16:17] neg_lo:[1,0,0] neg_hi:[1,0,0]
	v_pk_fma_f32 v[18:19], v[18:19], v[194:195], v[18:19] neg_lo:[1,0,0] neg_hi:[1,0,0]
	v_cvt_pk_bf16_f32 v164, v20, v21
	v_cvt_pk_bf16_f32 v165, v22, v23
	v_cvt_pk_bf16_f32 v166, v16, v17
	v_cvt_pk_bf16_f32 v167, v18, v19
	global_store_dwordx4 v[208:209], v[164:167], off offset:256 sc1
	v_pk_fma_f32 v[12:13], v[12:13], v[158:159], v[32:33] op_sel_hi:[1,0,1]
	v_pk_fma_f32 v[14:15], v[14:15], v[158:159], v[34:35] op_sel_hi:[1,0,1]
	v_pk_fma_f32 v[8:9], v[8:9], v[158:159], v[36:37] op_sel_hi:[1,0,1]
	v_pk_fma_f32 v[10:11], v[10:11], v[158:159], v[38:39] op_sel_hi:[1,0,1]
	v_lshl_add_u64 v[208:209], v[208:209], 0, s[42:43]
	v_pk_mul_f32 v[180:181], v[12:13], v[12:13]
	v_pk_mul_f32 v[182:183], v[14:15], v[14:15]
	v_pk_mul_f32 v[184:185], v[8:9], v[8:9]
	v_pk_mul_f32 v[186:187], v[10:11], v[10:11]
	v_pk_fma_f32 v[180:181], v[180:181], v[200:201], v[206:207] op_sel_hi:[1,0,0]
	v_pk_fma_f32 v[182:183], v[182:183], v[200:201], v[206:207] op_sel_hi:[1,0,0]
	v_pk_fma_f32 v[184:185], v[184:185], v[200:201], v[206:207] op_sel_hi:[1,0,0]
	v_pk_fma_f32 v[186:187], v[186:187], v[200:201], v[206:207] op_sel_hi:[1,0,0]
	v_pk_mul_f32 v[180:181], v[180:181], v[12:13]
	v_pk_mul_f32 v[182:183], v[182:183], v[14:15]
	v_pk_mul_f32 v[184:185], v[184:185], v[8:9]
	v_pk_mul_f32 v[186:187], v[186:187], v[10:11]
	v_exp_f32_e32 v188, v180
	v_exp_f32_e32 v189, v181
	v_exp_f32_e32 v190, v182
	v_exp_f32_e32 v191, v183
	v_exp_f32_e32 v192, v184
	v_exp_f32_e32 v193, v185
	v_exp_f32_e32 v194, v186
	v_exp_f32_e32 v195, v187
	v_pk_add_f32 v[188:189], v[188:189], v[196:197] op_sel_hi:[1,0]
	v_pk_add_f32 v[190:191], v[190:191], v[196:197] op_sel_hi:[1,0]
	v_pk_add_f32 v[192:193], v[192:193], v[196:197] op_sel_hi:[1,0]
	v_pk_add_f32 v[194:195], v[194:195], v[196:197] op_sel_hi:[1,0]
	v_rcp_f32_e32 v188, v188
	v_rcp_f32_e32 v189, v189
	v_rcp_f32_e32 v190, v190
	v_rcp_f32_e32 v191, v191
	v_rcp_f32_e32 v192, v192
	v_rcp_f32_e32 v193, v193
	v_rcp_f32_e32 v194, v194
	v_rcp_f32_e32 v195, v195
	s_nop 0
	v_pk_fma_f32 v[12:13], v[12:13], v[188:189], v[12:13] neg_lo:[1,0,0] neg_hi:[1,0,0]
	v_pk_fma_f32 v[14:15], v[14:15], v[190:191], v[14:15] neg_lo:[1,0,0] neg_hi:[1,0,0]
	v_pk_fma_f32 v[8:9], v[8:9], v[192:193], v[8:9] neg_lo:[1,0,0] neg_hi:[1,0,0]
	v_pk_fma_f32 v[10:11], v[10:11], v[194:195], v[10:11] neg_lo:[1,0,0] neg_hi:[1,0,0]
	v_cvt_pk_bf16_f32 v160, v12, v13
	v_cvt_pk_bf16_f32 v161, v14, v15
	v_cvt_pk_bf16_f32 v162, v8, v9
	v_cvt_pk_bf16_f32 v163, v10, v11
	global_store_dwordx4 v[208:209], v[160:163], off sc1
	v_pk_fma_f32 v[4:5], v[4:5], v[158:159], v[40:41] op_sel_hi:[1,0,1]
	v_pk_fma_f32 v[6:7], v[6:7], v[158:159], v[42:43] op_sel_hi:[1,0,1]
	v_pk_fma_f32 v[0:1], v[0:1], v[158:159], v[44:45] op_sel_hi:[1,0,1]
	v_pk_fma_f32 v[2:3], v[2:3], v[158:159], v[46:47] op_sel_hi:[1,0,1]
	v_pk_mul_f32 v[180:181], v[4:5], v[4:5]
	v_pk_mul_f32 v[182:183], v[6:7], v[6:7]
	v_pk_mul_f32 v[184:185], v[0:1], v[0:1]
	v_pk_mul_f32 v[186:187], v[2:3], v[2:3]
	v_pk_fma_f32 v[180:181], v[180:181], v[200:201], v[206:207] op_sel_hi:[1,0,0]
	v_pk_fma_f32 v[182:183], v[182:183], v[200:201], v[206:207] op_sel_hi:[1,0,0]
	v_pk_fma_f32 v[184:185], v[184:185], v[200:201], v[206:207] op_sel_hi:[1,0,0]
	v_pk_fma_f32 v[186:187], v[186:187], v[200:201], v[206:207] op_sel_hi:[1,0,0]
	v_pk_mul_f32 v[180:181], v[180:181], v[4:5]
	v_pk_mul_f32 v[182:183], v[182:183], v[6:7]
	v_pk_mul_f32 v[184:185], v[184:185], v[0:1]
	v_pk_mul_f32 v[186:187], v[186:187], v[2:3]
	v_exp_f32_e32 v188, v180
	v_exp_f32_e32 v189, v181
	v_exp_f32_e32 v190, v182
	v_exp_f32_e32 v191, v183
	v_exp_f32_e32 v192, v184
	v_exp_f32_e32 v193, v185
	v_exp_f32_e32 v194, v186
	v_exp_f32_e32 v195, v187
	v_pk_add_f32 v[188:189], v[188:189], v[196:197] op_sel_hi:[1,0]
	v_pk_add_f32 v[190:191], v[190:191], v[196:197] op_sel_hi:[1,0]
	v_pk_add_f32 v[192:193], v[192:193], v[196:197] op_sel_hi:[1,0]
	v_pk_add_f32 v[194:195], v[194:195], v[196:197] op_sel_hi:[1,0]
	v_rcp_f32_e32 v188, v188
	v_rcp_f32_e32 v189, v189
	v_rcp_f32_e32 v190, v190
	v_rcp_f32_e32 v191, v191
	v_rcp_f32_e32 v192, v192
	v_rcp_f32_e32 v193, v193
	v_rcp_f32_e32 v194, v194
	v_rcp_f32_e32 v195, v195
	s_nop 0
	v_pk_fma_f32 v[4:5], v[4:5], v[188:189], v[4:5] neg_lo:[1,0,0] neg_hi:[1,0,0]
	v_pk_fma_f32 v[6:7], v[6:7], v[190:191], v[6:7] neg_lo:[1,0,0] neg_hi:[1,0,0]
	v_pk_fma_f32 v[0:1], v[0:1], v[192:193], v[0:1] neg_lo:[1,0,0] neg_hi:[1,0,0]
	v_pk_fma_f32 v[2:3], v[2:3], v[194:195], v[2:3] neg_lo:[1,0,0] neg_hi:[1,0,0]
	v_cvt_pk_bf16_f32 v164, v4, v5
	v_cvt_pk_bf16_f32 v165, v6, v7
	v_cvt_pk_bf16_f32 v166, v0, v1
	v_cvt_pk_bf16_f32 v167, v2, v3
	global_store_dwordx4 v[208:209], v[164:167], off offset:256 sc1
